# nt hint on the in-projection epilogue stores (on top of v52)
# baseline (speedup 1.0000x reference)
; __device__ __forceinline__ unsigned cvt_pk_bf16(float lo, float hi) { unsigned r; asm volatile("v_cvt_pk_bf16_f32 %0, %1, %2" : "=v"(r) : "v"(lo), "v"(hi)); return r; }
; __device__ __forceinline__ float dpp_ror1(float x)  { return __builtin_bit_cast(float, __builtin_amdgcn_update_dpp(0, __builtin_bit_cast(int, x), 0x121, 0xF, 0xF, false)); }
; __device__ __forceinline__ float dpp_ror15(float x) { return __builtin_bit_cast(float, __builtin_amdgcn_update_dpp(0, __builtin_bit_cast(int, x), 0x12F, 0xF, 0xF, false)); }
;     __host__ __device__ bool next(int i, Unit& u) const { const long L = (long)i * G + c; if (L >= nwg) return false; u.pm = 0; u.pn = c % nN; return true; }
;     __device__ __forceinline__ void operator()(const f32x4 (&acc)[2][2][4][2], const Unit& u, int wr, int wc, int fr, int fq) const {
;     ...
;             typedef unsigned u32x2 __attribute__((ext_vector_type(2)));
;             const int ch0 = 64 * (u.pn - 12) + 16 * wc + 4 * fq;
;             const f32x4 w0 = *(const f32x4*)(convw + ch0), w1 = *(const f32x4*)(convw + nconv + ch0), w2 = *(const f32x4*)(convw + 2 * nconv + ch0);
; #pragma unroll
;             for (int ai = 0; ai < 2; ++ai) {
;                 f32x4 cv[4], rr[4], ll[4];
; #pragma unroll
;                 for (int m = 0; m < 4; ++m) { cv[m] = acc[ai][0][m][0] * acc[ai][0][m][1];
; #pragma unroll
;                     for (int e = 0; e < 4; ++e) { rr[m][e] = dpp_ror1(cv[m][e]); ll[m][e] = dpp_ror15(cv[m][e]); } }
; #pragma unroll
;                 for (int m = 0; m < 4; ++m) {
;                     const f32x4 z = (f32x4){0.f, 0.f, 0.f, 0.f};
;                     const f32x4 prev = fr > 0 ? rr[m] : (m > 0 ? rr[m > 0 ? m - 1 : 0] : z), next = fr < 15 ? ll[m] : (m < 3 ? ll[m < 3 ? m + 1 : 3] : z);
;                     const f32x4 o = acc[ai][1][m][0] * (w0 * prev + w1 * cv[m] + w2 * next);
;                     const f32x4 gq = acc[ai][1][m][1]; f32x4 gs;
; #pragma unroll
;                     for (int e = 0; e < 4; ++e) gs[e] = gq[e] * __builtin_amdgcn_rcpf(1.f + __expf(-gq[e]));
;                     const size_t r = (size_t)(row0 + ai * HALF + m * 16);
;                     *(u32x2*)(CATc + r * ldcat + ch0) = (u32x2){cvt_pk_bf16(o[0], o[1]), cvt_pk_bf16(o[2], o[3])};
;                     *(u32x2*)(GS + r * ldg + ch0) = (u32x2){cvt_pk_bf16(gs[0], gs[1]), cvt_pk_bf16(gs[2], gs[3])};
;                 }
;             }
.LBB0_261:
	v_lshl_add_u32 v172, s52, 6, v223
	v_lshlrev_b64 v[130:131], 2, v[172:173]
	v_lshl_add_u64 v[132:133], s[62:63], 0, v[130:131]
	v_lshl_add_u64 v[134:135], s[72:73], 0, v[130:131]
	global_load_dwordx4 v[138:141], v[132:133], off
	s_nop 0
	global_load_dwordx4 v[134:137], v[134:135], off
	v_lshl_add_u64 v[130:131], s[74:75], 0, v[130:131]
	global_load_dwordx4 v[130:133], v[130:131], off
	v_pk_mul_f32 v[142:143], v[128:129], v[124:125]
	v_mov_b32_e32 v201, v173
	v_mov_b32_e32 v212, v173
	v_mov_b32_e32 v203, v173
	v_mov_b32_dpp v201, v142 row_ror:1 row_mask:0xf bank_mask:0xf
	v_mov_b32_dpp v212, v143 row_ror:1 row_mask:0xf bank_mask:0xf
	v_cndmask_b32_e64 v159, v212, 0, s[4:5]
	v_cndmask_b32_e64 v158, v201, 0, s[4:5]
	v_mov_b32_e32 v204, v173
	v_pk_mul_f32 v[148:149], v[126:127], v[122:123]
	v_mov_b32_e32 v195, v173
	v_mov_b32_e32 v197, v173
	v_mov_b32_dpp v203, v142 row_ror:15 row_mask:0xf bank_mask:0xf
	v_mov_b32_dpp v204, v143 row_ror:15 row_mask:0xf bank_mask:0xf
	v_mov_b32_dpp v195, v148 row_ror:1 row_mask:0xf bank_mask:0xf
	v_mov_b32_dpp v197, v149 row_ror:1 row_mask:0xf bank_mask:0xf
	v_cndmask_b32_e64 v161, v197, 0, s[4:5]
	v_cndmask_b32_e64 v160, v195, 0, s[4:5]
	v_mov_b32_e32 v193, v173
	v_mov_b32_e32 v199, v173
	v_pk_mul_f32 v[150:151], v[112:113], v[108:109]
	v_mov_b32_dpp v193, v148 row_ror:15 row_mask:0xf bank_mask:0xf
	v_mov_b32_dpp v199, v149 row_ror:15 row_mask:0xf bank_mask:0xf
	v_pk_mul_f32 v[152:153], v[110:111], v[106:107]
	v_mov_b32_e32 v230, v173
	v_mov_b32_e32 v232, v173
	v_mov_b32_e32 v234, v173
	v_mov_b32_e32 v236, v173
	v_mov_b32_dpp v230, v152 row_ror:15 row_mask:0xf bank_mask:0xf
	v_mov_b32_dpp v232, v153 row_ror:15 row_mask:0xf bank_mask:0xf
	v_mov_b32_dpp v234, v150 row_ror:15 row_mask:0xf bank_mask:0xf
	v_mov_b32_dpp v236, v151 row_ror:15 row_mask:0xf bank_mask:0xf
	v_cndmask_b32_e64 v205, v204, v236, s[6:7]
	v_cndmask_b32_e64 v204, v203, v234, s[6:7]
	v_cndmask_b32_e64 v207, v199, v232, s[6:7]
	v_cndmask_b32_e64 v206, v193, v230, s[6:7]
	v_ashrrev_i32_e32 v193, 31, v192
	v_mov_b32_e32 v213, v173
	v_mov_b32_e32 v231, v173
	v_mov_b32_e32 v233, v173
	v_mov_b32_e32 v235, v173
	v_mov_b32_dpp v213, v152 row_ror:1 row_mask:0xf bank_mask:0xf
	v_mov_b32_dpp v231, v153 row_ror:1 row_mask:0xf bank_mask:0xf
	v_mov_b32_dpp v233, v150 row_ror:1 row_mask:0xf bank_mask:0xf
	v_mov_b32_dpp v235, v151 row_ror:1 row_mask:0xf bank_mask:0xf
	v_pk_mul_f32 v[154:155], v[96:97], v[92:93]
	v_pk_mul_f32 v[156:157], v[94:95], v[90:91]
	v_mov_b32_e32 v238, v173
	v_mov_b32_e32 v240, v173
	v_mov_b32_e32 v242, v173
	v_mov_b32_e32 v244, v173
	v_mov_b32_dpp v238, v156 row_ror:15 row_mask:0xf bank_mask:0xf
	v_mov_b32_dpp v240, v157 row_ror:15 row_mask:0xf bank_mask:0xf
	v_mov_b32_dpp v242, v154 row_ror:15 row_mask:0xf bank_mask:0xf
	v_mov_b32_dpp v244, v155 row_ror:15 row_mask:0xf bank_mask:0xf
	v_mov_b32_e32 v241, v173
	v_mov_b32_e32 v243, v173
	v_mov_b32_e32 v237, v173
	v_mov_b32_dpp v241, v154 row_ror:1 row_mask:0xf bank_mask:0xf
	v_mov_b32_dpp v243, v155 row_ror:1 row_mask:0xf bank_mask:0xf
	v_mov_b32_e32 v239, v173
	v_pk_mul_f32 v[144:145], v[80:81], v[76:77]
	v_mov_b32_e32 v250, v173
	v_mov_b32_e32 v252, v173
	v_mov_b32_dpp v237, v156 row_ror:1 row_mask:0xf bank_mask:0xf
	v_mov_b32_dpp v239, v157 row_ror:1 row_mask:0xf bank_mask:0xf
	v_mov_b32_dpp v250, v144 row_ror:15 row_mask:0xf bank_mask:0xf
	v_mov_b32_dpp v252, v145 row_ror:15 row_mask:0xf bank_mask:0xf
	v_pk_mul_f32 v[146:147], v[78:79], v[74:75]
	v_mov_b32_e32 v246, v173
	v_mov_b32_e32 v248, v173
	v_mov_b32_e32 v245, v173
	v_mov_b32_dpp v246, v146 row_ror:15 row_mask:0xf bank_mask:0xf
	v_mov_b32_dpp v248, v147 row_ror:15 row_mask:0xf bank_mask:0xf
	v_mov_b32_e32 v247, v173
	v_mov_b32_dpp v245, v146 row_ror:1 row_mask:0xf bank_mask:0xf
	s_waitcnt vmcnt(0)
	v_pk_mul_f32 v[158:159], v[140:141], v[158:159]
	v_pk_mul_f32 v[160:161], v[138:139], v[160:161]
	v_pk_fma_f32 v[142:143], v[142:143], v[136:137], v[158:159]
	v_mul_f32_e32 v158, 0xbfb8aa3b, v114
	v_mul_f32_e32 v159, 0xbfb8aa3b, v115
	v_exp_f32_e32 v158, v158
	v_exp_f32_e32 v159, v159
	v_pk_fma_f32 v[148:149], v[148:149], v[134:135], v[160:161]
	v_mul_f32_e32 v160, 0xbfb8aa3b, v116
	v_mul_f32_e32 v161, 0xbfb8aa3b, v117
	v_add_f32_e32 v158, 1.0, v158
	v_add_f32_e32 v159, 1.0, v159
	v_exp_f32_e32 v160, v160
	v_exp_f32_e32 v161, v161
	v_rcp_f32_e32 v158, v158
	v_rcp_f32_e32 v159, v159
	v_pk_fma_f32 v[142:143], v[132:133], v[204:205], v[142:143]
	v_pk_fma_f32 v[148:149], v[130:131], v[206:207], v[148:149]
	v_pk_mul_f32 v[142:143], v[120:121], v[142:143]
	v_pk_mul_f32 v[148:149], v[118:119], v[148:149]
	v_add_f32_e32 v160, 1.0, v160
	v_add_f32_e32 v161, 1.0, v161
	v_cvt_pk_bf16_f32 v148, v148, v149
	v_cvt_pk_bf16_f32 v149, v142, v143
	v_lshlrev_b64 v[142:143], 12, v[192:193]
	v_rcp_f32_e32 v160, v160
	v_rcp_f32_e32 v161, v161
	v_mul_f32_e32 v199, v114, v158
	v_mul_f32_e32 v203, v115, v159
	v_lshl_add_u64 v[158:159], s[66:67], 0, v[142:143]
	v_lshlrev_b64 v[142:143], 1, v[172:173]
	v_lshl_add_u64 v[158:159], v[158:159], 0, v[142:143]
	global_store_dwordx2 v[158:159], v[148:149], off nt
	v_lshlrev_b64 v[158:159], 11, v[192:193]
	v_lshl_add_u64 v[158:159], s[48:49], 0, v[158:159]
	v_mul_f32_e32 v160, v116, v160
	v_mul_f32_e32 v161, v117, v161
	v_cvt_pk_bf16_f32 v148, v199, v203
	v_cvt_pk_bf16_f32 v149, v160, v161
	v_lshl_add_u64 v[158:159], v[158:159], 0, v[142:143]
	global_store_dwordx2 v[158:159], v[148:149], off nt
	v_cndmask_b32_e64 v149, v235, v212, s[4:5]
	v_cndmask_b32_e64 v148, v233, v201, s[4:5]
	v_cndmask_b32_e64 v159, v231, v197, s[4:5]
	v_cndmask_b32_e64 v158, v213, v195, s[4:5]
	v_pk_mul_f32 v[148:149], v[140:141], v[148:149]
; __device__ __forceinline__ unsigned cvt_pk_bf16(float lo, float hi) { unsigned r; asm volatile("v_cvt_pk_bf16_f32 %0, %1, %2" : "=v"(r) : "v"(lo), "v"(hi)); return r; }
; __device__ __forceinline__ float dpp_ror1(float x)  { return __builtin_bit_cast(float, __builtin_amdgcn_update_dpp(0, __builtin_bit_cast(int, x), 0x121, 0xF, 0xF, false)); }
; __device__ __forceinline__ float dpp_ror15(float x) { return __builtin_bit_cast(float, __builtin_amdgcn_update_dpp(0, __builtin_bit_cast(int, x), 0x12F, 0xF, 0xF, false)); }
;     __host__ __device__ bool next(int i, Unit& u) const { const long L = (long)i * G + c; if (L >= nwg) return false; u.pm = 0; u.pn = c % nN; return true; }
;     __device__ __forceinline__ void operator()(const f32x4 (&acc)[2][2][4][2], const Unit& u, int wr, int wc, int fr, int fq) const {
;     ...
;                 for (int m = 0; m < 4; ++m) { cv[m] = acc[ai][0][m][0] * acc[ai][0][m][1];
; #pragma unroll
;                     for (int e = 0; e < 4; ++e) { rr[m][e] = dpp_ror1(cv[m][e]); ll[m][e] = dpp_ror15(cv[m][e]); } }
; #pragma unroll
;                 for (int m = 0; m < 4; ++m) {
;                     const f32x4 z = (f32x4){0.f, 0.f, 0.f, 0.f};
;                     const f32x4 prev = fr > 0 ? rr[m] : (m > 0 ? rr[m > 0 ? m - 1 : 0] : z), next = fr < 15 ? ll[m] : (m < 3 ? ll[m < 3 ? m + 1 : 3] : z);
;                     const f32x4 o = acc[ai][1][m][0] * (w0 * prev + w1 * cv[m] + w2 * next);
;                     const f32x4 gq = acc[ai][1][m][1]; f32x4 gs;
; #pragma unroll
;                     for (int e = 0; e < 4; ++e) gs[e] = gq[e] * __builtin_amdgcn_rcpf(1.f + __expf(-gq[e]));
;                     const size_t r = (size_t)(row0 + ai * HALF + m * 16);
;                     *(u32x2*)(CATc + r * ldcat + ch0) = (u32x2){cvt_pk_bf16(o[0], o[1]), cvt_pk_bf16(o[2], o[3])};
;                     *(u32x2*)(GS + r * ldg + ch0) = (u32x2){cvt_pk_bf16(gs[0], gs[1]), cvt_pk_bf16(gs[2], gs[3])};
	v_pk_mul_f32 v[158:159], v[138:139], v[158:159]
	v_pk_fma_f32 v[148:149], v[150:151], v[136:137], v[148:149]
	v_pk_fma_f32 v[150:151], v[152:153], v[134:135], v[158:159]
	v_mul_f32_e32 v152, 0xbfb8aa3b, v98
	v_mul_f32_e32 v153, 0xbfb8aa3b, v99
	v_mul_f32_e32 v158, 0xbfb8aa3b, v100
	v_mul_f32_e32 v159, 0xbfb8aa3b, v101
	v_exp_f32_e32 v152, v152
	v_exp_f32_e32 v153, v153
	v_exp_f32_e32 v158, v158
	v_exp_f32_e32 v159, v159
	v_cndmask_b32_e64 v161, v236, v244, s[6:7]
	v_cndmask_b32_e64 v160, v234, v242, s[6:7]
	v_cndmask_b32_e64 v205, v232, v240, s[6:7]
	v_cndmask_b32_e64 v204, v230, v238, s[6:7]
	v_pk_fma_f32 v[148:149], v[132:133], v[160:161], v[148:149]
	v_pk_fma_f32 v[150:151], v[130:131], v[204:205], v[150:151]
	v_pk_mul_f32 v[148:149], v[104:105], v[148:149]
	v_pk_mul_f32 v[150:151], v[102:103], v[150:151]
	v_ashrrev_i32_e32 v203, 31, v202
	v_add_f32_e32 v152, 1.0, v152
	v_add_f32_e32 v153, 1.0, v153
	v_add_f32_e32 v158, 1.0, v158
	v_add_f32_e32 v159, 1.0, v159
	v_cvt_pk_bf16_f32 v150, v150, v151
	v_cvt_pk_bf16_f32 v151, v148, v149
	v_lshlrev_b64 v[148:149], 12, v[202:203]
	v_rcp_f32_e32 v152, v152
	v_rcp_f32_e32 v153, v153
	v_rcp_f32_e32 v158, v158
	v_rcp_f32_e32 v159, v159
	v_lshl_add_u64 v[148:149], s[66:67], 0, v[148:149]
	v_lshl_add_u64 v[148:149], v[148:149], 0, v[142:143]
	global_store_dwordx2 v[148:149], v[150:151], off nt
	v_lshlrev_b64 v[150:151], 11, v[202:203]
	v_lshl_add_u64 v[150:151], s[48:49], 0, v[150:151]
	v_mul_f32_e32 v152, v98, v152
	v_mul_f32_e32 v153, v99, v153
	v_mul_f32_e32 v158, v100, v158
	v_mul_f32_e32 v159, v101, v159
	v_cvt_pk_bf16_f32 v148, v152, v153
	v_cvt_pk_bf16_f32 v149, v158, v159
	v_lshl_add_u64 v[150:151], v[150:151], 0, v[142:143]
	global_store_dwordx2 v[150:151], v[148:149], off nt
	v_cndmask_b32_e64 v149, v243, v235, s[4:5]
	v_cndmask_b32_e64 v148, v241, v233, s[4:5]
	v_pk_mul_f32 v[148:149], v[140:141], v[148:149]
	v_cndmask_b32_e64 v151, v239, v231, s[4:5]
	v_cndmask_b32_e64 v150, v237, v213, s[4:5]
	v_cndmask_b32_e64 v153, v244, v252, s[6:7]
	v_cndmask_b32_e64 v152, v242, v250, s[6:7]
	v_pk_fma_f32 v[148:149], v[154:155], v[136:137], v[148:149]
	v_pk_mul_f32 v[150:151], v[138:139], v[150:151]
	v_pk_fma_f32 v[148:149], v[132:133], v[152:153], v[148:149]
	v_mul_f32_e32 v152, 0xbfb8aa3b, v82
	v_mul_f32_e32 v153, 0xbfb8aa3b, v83
	v_mul_f32_e32 v154, 0xbfb8aa3b, v84
	v_mul_f32_e32 v155, 0xbfb8aa3b, v85
	v_cndmask_b32_e64 v159, v240, v248, s[6:7]
	v_cndmask_b32_e64 v158, v238, v246, s[6:7]
	v_pk_fma_f32 v[150:151], v[156:157], v[134:135], v[150:151]
	v_exp_f32_e32 v152, v152
	v_exp_f32_e32 v153, v153
	v_exp_f32_e32 v154, v154
	v_exp_f32_e32 v155, v155
	v_pk_fma_f32 v[150:151], v[130:131], v[158:159], v[150:151]
	v_pk_mul_f32 v[148:149], v[88:89], v[148:149]
	v_pk_mul_f32 v[150:151], v[86:87], v[150:151]
	v_ashrrev_i32_e32 v201, 31, v200
	v_cvt_pk_bf16_f32 v150, v150, v151
	v_cvt_pk_bf16_f32 v151, v148, v149
	v_lshlrev_b64 v[148:149], 12, v[200:201]
	v_add_f32_e32 v152, 1.0, v152
	v_add_f32_e32 v153, 1.0, v153
	v_add_f32_e32 v154, 1.0, v154
	v_add_f32_e32 v155, 1.0, v155
	v_lshl_add_u64 v[148:149], s[66:67], 0, v[148:149]
	v_rcp_f32_e32 v152, v152
	v_rcp_f32_e32 v153, v153
	v_rcp_f32_e32 v154, v154
	v_rcp_f32_e32 v155, v155
	v_lshl_add_u64 v[148:149], v[148:149], 0, v[142:143]
	global_store_dwordx2 v[148:149], v[150:151], off nt
	v_lshlrev_b64 v[150:151], 11, v[200:201]
	v_lshl_add_u64 v[150:151], s[48:49], 0, v[150:151]
	v_mov_b32_dpp v247, v147 row_ror:1 row_mask:0xf bank_mask:0xf
	v_mov_b32_e32 v249, v173
	v_mov_b32_e32 v251, v173
	v_lshl_add_u64 v[150:151], v[150:151], 0, v[142:143]
	v_mov_b32_dpp v249, v144 row_ror:1 row_mask:0xf bank_mask:0xf
	v_mov_b32_dpp v251, v145 row_ror:1 row_mask:0xf bank_mask:0xf
	v_mul_f32_e32 v152, v82, v152
	v_mul_f32_e32 v153, v83, v153
	v_mul_f32_e32 v154, v84, v154
	v_mul_f32_e32 v155, v85, v155
	v_cvt_pk_bf16_f32 v148, v152, v153
	v_cvt_pk_bf16_f32 v149, v154, v155
	global_store_dwordx2 v[150:151], v[148:149], off nt
	v_cndmask_b32_e64 v151, v247, v239, s[4:5]
	v_cndmask_b32_e64 v150, v245, v237, s[4:5]
	v_cndmask_b32_e64 v149, v251, v243, s[4:5]
	v_cndmask_b32_e64 v148, v249, v241, s[4:5]
	v_pk_mul_f32 v[150:151], v[138:139], v[150:151]
	v_pk_mul_f32 v[148:149], v[140:141], v[148:149]
	v_pk_fma_f32 v[146:147], v[146:147], v[134:135], v[150:151]
	v_mul_f32_e32 v150, 0xbfb8aa3b, v68
	v_mul_f32_e32 v151, 0xbfb8aa3b, v69
	v_pk_fma_f32 v[144:145], v[144:145], v[136:137], v[148:149]
	v_mul_f32_e32 v148, 0xbfb8aa3b, v66
	v_mul_f32_e32 v149, 0xbfb8aa3b, v67
	v_exp_f32_e32 v150, v150
	v_exp_f32_e32 v151, v151
	v_exp_f32_e32 v148, v148
	v_exp_f32_e32 v149, v149
	v_cndmask_b32_e64 v153, v252, 0, s[6:7]
	v_cndmask_b32_e64 v152, v250, 0, s[6:7]
	v_cndmask_b32_e64 v155, v248, 0, s[6:7]
	v_cndmask_b32_e64 v154, v246, 0, s[6:7]
	v_add_f32_e32 v150, 1.0, v150
	v_add_f32_e32 v151, 1.0, v151
	v_pk_fma_f32 v[144:145], v[132:133], v[152:153], v[144:145]
	v_pk_fma_f32 v[146:147], v[130:131], v[154:155], v[146:147]
	v_add_f32_e32 v148, 1.0, v148
	v_add_f32_e32 v149, 1.0, v149
	v_rcp_f32_e32 v150, v150
	v_rcp_f32_e32 v151, v151
	v_rcp_f32_e32 v148, v148
	v_rcp_f32_e32 v149, v149
	v_pk_mul_f32 v[144:145], v[72:73], v[144:145]
	v_pk_mul_f32 v[146:147], v[70:71], v[146:147]
	v_ashrrev_i32_e32 v199, 31, v198
	v_cvt_pk_bf16_f32 v146, v146, v147
	v_cvt_pk_bf16_f32 v147, v144, v145
	v_lshlrev_b64 v[144:145], 12, v[198:199]
	v_lshl_add_u64 v[144:145], s[66:67], 0, v[144:145]
	v_mul_f32_e32 v150, v68, v150
	v_mul_f32_e32 v151, v69, v151
	v_lshl_add_u64 v[144:145], v[144:145], 0, v[142:143]
	v_mul_f32_e32 v148, v66, v148
	v_mul_f32_e32 v149, v67, v149
	global_store_dwordx2 v[144:145], v[146:147], off nt
; __device__ __forceinline__ unsigned cvt_pk_bf16(float lo, float hi) { unsigned r; asm volatile("v_cvt_pk_bf16_f32 %0, %1, %2" : "=v"(r) : "v"(lo), "v"(hi)); return r; }
; __device__ __forceinline__ float dpp_ror1(float x)  { return __builtin_bit_cast(float, __builtin_amdgcn_update_dpp(0, __builtin_bit_cast(int, x), 0x121, 0xF, 0xF, false)); }
; __device__ __forceinline__ float dpp_ror15(float x) { return __builtin_bit_cast(float, __builtin_amdgcn_update_dpp(0, __builtin_bit_cast(int, x), 0x12F, 0xF, 0xF, false)); }
;     __host__ __device__ bool next(int i, Unit& u) const { const long L = (long)i * G + c; if (L >= nwg) return false; u.pm = 0; u.pn = c % nN; return true; }
;     __device__ __forceinline__ void operator()(const f32x4 (&acc)[2][2][4][2], const Unit& u, int wr, int wc, int fr, int fq) const {
;     ...
;                 for (int m = 0; m < 4; ++m) { cv[m] = acc[ai][0][m][0] * acc[ai][0][m][1];
; #pragma unroll
;                     for (int e = 0; e < 4; ++e) { rr[m][e] = dpp_ror1(cv[m][e]); ll[m][e] = dpp_ror15(cv[m][e]); } }
; #pragma unroll
;                 for (int m = 0; m < 4; ++m) {
;                     const f32x4 z = (f32x4){0.f, 0.f, 0.f, 0.f};
;                     const f32x4 prev = fr > 0 ? rr[m] : (m > 0 ? rr[m > 0 ? m - 1 : 0] : z), next = fr < 15 ? ll[m] : (m < 3 ? ll[m < 3 ? m + 1 : 3] : z);
;                     const f32x4 o = acc[ai][1][m][0] * (w0 * prev + w1 * cv[m] + w2 * next);
;                     const f32x4 gq = acc[ai][1][m][1]; f32x4 gs;
; #pragma unroll
;                     for (int e = 0; e < 4; ++e) gs[e] = gq[e] * __builtin_amdgcn_rcpf(1.f + __expf(-gq[e]));
;                     const size_t r = (size_t)(row0 + ai * HALF + m * 16);
;                     *(u32x2*)(CATc + r * ldcat + ch0) = (u32x2){cvt_pk_bf16(o[0], o[1]), cvt_pk_bf16(o[2], o[3])};
;                     *(u32x2*)(GS + r * ldg + ch0) = (u32x2){cvt_pk_bf16(gs[0], gs[1]), cvt_pk_bf16(gs[2], gs[3])};
	v_cvt_pk_bf16_f32 v144, v148, v149
	v_cvt_pk_bf16_f32 v145, v150, v151
	v_pk_mul_f32 v[150:151], v[62:63], v[58:59]
	v_mov_b32_e32 v197, v173
	v_pk_mul_f32 v[154:155], v[46:47], v[42:43]
	v_mov_b32_e32 v233, v173
	v_mov_b32_dpp v197, v151 row_ror:15 row_mask:0xf bank_mask:0xf
	v_lshlrev_b64 v[146:147], 11, v[198:199]
	v_mov_b32_dpp v233, v155 row_ror:15 row_mask:0xf bank_mask:0xf
	v_cndmask_b32_e64 v213, v197, v233, s[6:7]
	v_mul_f32_e32 v197, 0xbfb8aa3b, v53
	v_exp_f32_e32 v197, v197
	v_pk_mul_f32 v[148:149], v[64:65], v[60:61]
	v_mov_b32_e32 v199, v173
	v_mov_b32_e32 v203, v173
	v_mov_b32_e32 v172, v173
	v_mov_b32_dpp v199, v148 row_ror:1 row_mask:0xf bank_mask:0xf
	v_mov_b32_dpp v203, v149 row_ror:1 row_mask:0xf bank_mask:0xf
	v_mov_b32_e32 v193, v173
	v_mov_b32_e32 v195, v173
	v_mov_b32_e32 v231, v173
	v_cndmask_b32_e64 v161, v203, 0, s[4:5]
	v_cndmask_b32_e64 v160, v199, 0, s[4:5]
	v_mov_b32_dpp v172, v150 row_ror:1 row_mask:0xf bank_mask:0xf
	v_mov_b32_dpp v193, v150 row_ror:15 row_mask:0xf bank_mask:0xf
	v_mov_b32_dpp v195, v151 row_ror:1 row_mask:0xf bank_mask:0xf
	v_mov_b32_e32 v201, v173
	v_mov_b32_e32 v206, v173
	v_mov_b32_dpp v231, v154 row_ror:15 row_mask:0xf bank_mask:0xf
	v_pk_mul_f32 v[160:161], v[140:141], v[160:161]
	v_add_f32_e32 v197, 1.0, v197
	v_mov_b32_dpp v201, v148 row_ror:15 row_mask:0xf bank_mask:0xf
	v_mov_b32_dpp v206, v149 row_ror:15 row_mask:0xf bank_mask:0xf
	v_pk_mul_f32 v[152:153], v[48:49], v[44:45]
	v_mov_b32_e32 v235, v173
	v_mov_b32_e32 v237, v173
	v_cndmask_b32_e64 v205, v195, 0, s[4:5]
	v_cndmask_b32_e64 v204, v172, 0, s[4:5]
	v_cndmask_b32_e64 v212, v193, v231, s[6:7]
	v_pk_fma_f32 v[148:149], v[148:149], v[136:137], v[160:161]
	v_mul_f32_e32 v160, 0xbfb8aa3b, v50
	v_mul_f32_e32 v161, 0xbfb8aa3b, v51
	v_mul_f32_e32 v193, 0xbfb8aa3b, v52
	v_rcp_f32_e32 v197, v197
	v_mov_b32_dpp v235, v152 row_ror:15 row_mask:0xf bank_mask:0xf
	v_mov_b32_dpp v237, v153 row_ror:15 row_mask:0xf bank_mask:0xf
	v_pk_mul_f32 v[204:205], v[138:139], v[204:205]
	v_exp_f32_e32 v160, v160
	v_exp_f32_e32 v161, v161
	v_exp_f32_e32 v193, v193
	v_cndmask_b32_e64 v207, v206, v237, s[6:7]
	v_cndmask_b32_e64 v206, v201, v235, s[6:7]
	v_pk_fma_f32 v[150:151], v[150:151], v[134:135], v[204:205]
	v_lshl_add_u64 v[146:147], s[48:49], 0, v[146:147]
	v_pk_fma_f32 v[148:149], v[132:133], v[206:207], v[148:149]
	v_pk_fma_f32 v[150:151], v[130:131], v[212:213], v[150:151]
	v_lshl_add_u64 v[146:147], v[146:147], 0, v[142:143]
	v_mul_f32_e32 v201, v53, v197
	v_pk_mul_f32 v[148:149], v[56:57], v[148:149]
	v_pk_mul_f32 v[150:151], v[54:55], v[150:151]
	v_ashrrev_i32_e32 v197, 31, v196
	global_store_dwordx2 v[146:147], v[144:145], off nt
	v_add_f32_e32 v160, 1.0, v160
	v_add_f32_e32 v161, 1.0, v161
	v_add_f32_e32 v193, 1.0, v193
	v_cvt_pk_bf16_f32 v150, v150, v151
	v_cvt_pk_bf16_f32 v151, v148, v149
	v_lshlrev_b64 v[148:149], 12, v[196:197]
	v_rcp_f32_e32 v160, v160
	v_rcp_f32_e32 v161, v161
	v_rcp_f32_e32 v193, v193
	v_lshl_add_u64 v[148:149], s[66:67], 0, v[148:149]
	v_lshl_add_u64 v[148:149], v[148:149], 0, v[142:143]
	global_store_dwordx2 v[148:149], v[150:151], off nt
	v_lshlrev_b64 v[150:151], 11, v[196:197]
	v_mov_b32_e32 v230, v173
	v_mov_b32_e32 v232, v173
	v_mov_b32_e32 v234, v173
	v_mov_b32_e32 v236, v173
	v_lshl_add_u64 v[150:151], s[48:49], 0, v[150:151]
	v_mov_b32_dpp v230, v154 row_ror:1 row_mask:0xf bank_mask:0xf
	v_mov_b32_dpp v232, v155 row_ror:1 row_mask:0xf bank_mask:0xf
	v_mov_b32_dpp v234, v152 row_ror:1 row_mask:0xf bank_mask:0xf
	v_mov_b32_dpp v236, v153 row_ror:1 row_mask:0xf bank_mask:0xf
	v_mul_f32_e32 v160, v50, v160
	v_mul_f32_e32 v161, v51, v161
	v_mul_f32_e32 v193, v52, v193
	v_cvt_pk_bf16_f32 v148, v160, v161
	v_cvt_pk_bf16_f32 v149, v193, v201
	v_lshl_add_u64 v[150:151], v[150:151], 0, v[142:143]
	global_store_dwordx2 v[150:151], v[148:149], off nt
	v_cndmask_b32_e64 v149, v236, v203, s[4:5]
	v_cndmask_b32_e64 v148, v234, v199, s[4:5]
	v_cndmask_b32_e64 v151, v232, v195, s[4:5]
	v_cndmask_b32_e64 v150, v230, v172, s[4:5]
	v_pk_mul_f32 v[148:149], v[140:141], v[148:149]
	v_pk_mul_f32 v[150:151], v[138:139], v[150:151]
	v_pk_mul_f32 v[156:157], v[32:33], v[28:29]
	v_pk_mul_f32 v[158:159], v[30:31], v[26:27]
	v_mov_b32_e32 v239, v173
	v_mov_b32_e32 v241, v173
	v_mov_b32_e32 v243, v173
	v_mov_b32_e32 v245, v173
	v_pk_fma_f32 v[148:149], v[152:153], v[136:137], v[148:149]
	v_pk_fma_f32 v[150:151], v[154:155], v[134:135], v[150:151]
	v_mul_f32_e32 v152, 0xbfb8aa3b, v34
	v_mul_f32_e32 v153, 0xbfb8aa3b, v35
	v_mul_f32_e32 v154, 0xbfb8aa3b, v36
	v_mul_f32_e32 v155, 0xbfb8aa3b, v37
	v_mov_b32_dpp v239, v158 row_ror:15 row_mask:0xf bank_mask:0xf
	v_mov_b32_dpp v241, v159 row_ror:15 row_mask:0xf bank_mask:0xf
	v_mov_b32_dpp v243, v156 row_ror:15 row_mask:0xf bank_mask:0xf
	v_mov_b32_dpp v245, v157 row_ror:15 row_mask:0xf bank_mask:0xf
	v_exp_f32_e32 v152, v152
	v_exp_f32_e32 v153, v153
	v_exp_f32_e32 v154, v154
	v_exp_f32_e32 v155, v155
	v_cndmask_b32_e64 v161, v237, v245, s[6:7]
	v_cndmask_b32_e64 v160, v235, v243, s[6:7]
	v_cndmask_b32_e64 v205, v233, v241, s[6:7]
	v_cndmask_b32_e64 v204, v231, v239, s[6:7]
	v_pk_fma_f32 v[148:149], v[132:133], v[160:161], v[148:149]
	v_pk_fma_f32 v[150:151], v[130:131], v[204:205], v[150:151]
	v_pk_mul_f32 v[148:149], v[40:41], v[148:149]
	v_pk_mul_f32 v[150:151], v[38:39], v[150:151]
	v_ashrrev_i32_e32 v195, 31, v194
	v_add_f32_e32 v152, 1.0, v152
	v_add_f32_e32 v153, 1.0, v153
	v_add_f32_e32 v154, 1.0, v154
	v_add_f32_e32 v155, 1.0, v155
	v_cvt_pk_bf16_f32 v150, v150, v151
	v_cvt_pk_bf16_f32 v151, v148, v149
	v_lshlrev_b64 v[148:149], 12, v[194:195]
	v_rcp_f32_e32 v152, v152
; __device__ __forceinline__ unsigned cvt_pk_bf16(float lo, float hi) { unsigned r; asm volatile("v_cvt_pk_bf16_f32 %0, %1, %2" : "=v"(r) : "v"(lo), "v"(hi)); return r; }
; __device__ __forceinline__ float dpp_ror1(float x)  { return __builtin_bit_cast(float, __builtin_amdgcn_update_dpp(0, __builtin_bit_cast(int, x), 0x121, 0xF, 0xF, false)); }
; __device__ __forceinline__ float dpp_ror15(float x) { return __builtin_bit_cast(float, __builtin_amdgcn_update_dpp(0, __builtin_bit_cast(int, x), 0x12F, 0xF, 0xF, false)); }
;     __host__ __device__ bool next(int i, Unit& u) const { const long L = (long)i * G + c; if (L >= nwg) return false; u.pm = 0; u.pn = c % nN; return true; }
;     __device__ __forceinline__ void operator()(const f32x4 (&acc)[2][2][4][2], const Unit& u, int wr, int wc, int fr, int fq) const {
;     ...
;                 for (int m = 0; m < 4; ++m) { cv[m] = acc[ai][0][m][0] * acc[ai][0][m][1];
; #pragma unroll
;                     for (int e = 0; e < 4; ++e) { rr[m][e] = dpp_ror1(cv[m][e]); ll[m][e] = dpp_ror15(cv[m][e]); } }
; #pragma unroll
;                 for (int m = 0; m < 4; ++m) {
;                     const f32x4 z = (f32x4){0.f, 0.f, 0.f, 0.f};
;                     const f32x4 prev = fr > 0 ? rr[m] : (m > 0 ? rr[m > 0 ? m - 1 : 0] : z), next = fr < 15 ? ll[m] : (m < 3 ? ll[m < 3 ? m + 1 : 3] : z);
;                     const f32x4 o = acc[ai][1][m][0] * (w0 * prev + w1 * cv[m] + w2 * next);
;                     const f32x4 gq = acc[ai][1][m][1]; f32x4 gs;
; #pragma unroll
;                     for (int e = 0; e < 4; ++e) gs[e] = gq[e] * __builtin_amdgcn_rcpf(1.f + __expf(-gq[e]));
;                     const size_t r = (size_t)(row0 + ai * HALF + m * 16);
;                     *(u32x2*)(CATc + r * ldcat + ch0) = (u32x2){cvt_pk_bf16(o[0], o[1]), cvt_pk_bf16(o[2], o[3])};
;                     *(u32x2*)(GS + r * ldg + ch0) = (u32x2){cvt_pk_bf16(gs[0], gs[1]), cvt_pk_bf16(gs[2], gs[3])};
	v_rcp_f32_e32 v153, v153
	v_rcp_f32_e32 v154, v154
	v_rcp_f32_e32 v155, v155
	v_lshl_add_u64 v[148:149], s[66:67], 0, v[148:149]
	v_lshl_add_u64 v[148:149], v[148:149], 0, v[142:143]
	global_store_dwordx2 v[148:149], v[150:151], off nt
	v_lshlrev_b64 v[150:151], 11, v[194:195]
	v_mov_b32_e32 v242, v173
	v_mov_b32_e32 v244, v173
	v_lshl_add_u64 v[150:151], s[48:49], 0, v[150:151]
	v_mov_b32_dpp v242, v156 row_ror:1 row_mask:0xf bank_mask:0xf
	v_mov_b32_dpp v244, v157 row_ror:1 row_mask:0xf bank_mask:0xf
	v_mul_f32_e32 v152, v34, v152
	v_mul_f32_e32 v153, v35, v153
	v_mul_f32_e32 v154, v36, v154
	v_mul_f32_e32 v155, v37, v155
	v_cvt_pk_bf16_f32 v148, v152, v153
	v_cvt_pk_bf16_f32 v149, v154, v155
	v_lshl_add_u64 v[150:151], v[150:151], 0, v[142:143]
	v_pk_mul_f32 v[144:145], v[16:17], v[12:13]
	v_mov_b32_e32 v251, v173
	v_mov_b32_e32 v253, v173
	global_store_dwordx2 v[150:151], v[148:149], off nt
	v_cndmask_b32_e64 v149, v244, v236, s[4:5]
	v_cndmask_b32_e64 v148, v242, v234, s[4:5]
	v_mov_b32_dpp v251, v144 row_ror:15 row_mask:0xf bank_mask:0xf
	v_mov_b32_dpp v253, v145 row_ror:15 row_mask:0xf bank_mask:0xf
	v_pk_mul_f32 v[148:149], v[140:141], v[148:149]
	v_cndmask_b32_e64 v153, v245, v253, s[6:7]
	v_cndmask_b32_e64 v152, v243, v251, s[6:7]
	v_pk_fma_f32 v[148:149], v[156:157], v[136:137], v[148:149]
	v_mov_b32_e32 v238, v173
	v_pk_fma_f32 v[148:149], v[132:133], v[152:153], v[148:149]
	v_mul_f32_e32 v152, 0xbfb8aa3b, v18
	v_exp_f32_e32 v152, v152
	v_mul_f32_e32 v153, 0xbfb8aa3b, v19
	v_mov_b32_e32 v240, v173
	v_exp_f32_e32 v153, v153
	v_mov_b32_dpp v238, v158 row_ror:1 row_mask:0xf bank_mask:0xf
	v_mov_b32_dpp v240, v159 row_ror:1 row_mask:0xf bank_mask:0xf
	v_pk_mul_f32 v[146:147], v[14:15], v[10:11]
	v_mov_b32_e32 v247, v173
	v_mov_b32_e32 v249, v173
	v_cndmask_b32_e64 v151, v240, v232, s[4:5]
	v_cndmask_b32_e64 v150, v238, v230, s[4:5]
	v_mov_b32_dpp v247, v146 row_ror:15 row_mask:0xf bank_mask:0xf
	v_mov_b32_dpp v249, v147 row_ror:15 row_mask:0xf bank_mask:0xf
	v_pk_mul_f32 v[150:151], v[138:139], v[150:151]
	v_add_f32_e32 v152, 1.0, v152
	v_cndmask_b32_e64 v155, v241, v249, s[6:7]
	v_cndmask_b32_e64 v154, v239, v247, s[6:7]
	v_pk_fma_f32 v[150:151], v[158:159], v[134:135], v[150:151]
	v_rcp_f32_e32 v152, v152
	v_add_f32_e32 v153, 1.0, v153
	v_pk_fma_f32 v[150:151], v[130:131], v[154:155], v[150:151]
	v_mul_f32_e32 v154, 0xbfb8aa3b, v20
	v_mul_f32_e32 v155, 0xbfb8aa3b, v21
	v_rcp_f32_e32 v153, v153
	v_exp_f32_e32 v154, v154
	v_exp_f32_e32 v155, v155
	v_mul_f32_e32 v156, v18, v152
	v_add_u32_e32 v152, 0xa0, v192
	v_mul_f32_e32 v157, v19, v153
	v_pk_mul_f32 v[148:149], v[24:25], v[148:149]
	v_pk_mul_f32 v[150:151], v[22:23], v[150:151]
	v_ashrrev_i32_e32 v153, 31, v152
	v_add_f32_e32 v154, 1.0, v154
	v_add_f32_e32 v155, 1.0, v155
	v_cvt_pk_bf16_f32 v150, v150, v151
	v_cvt_pk_bf16_f32 v151, v148, v149
	v_lshlrev_b64 v[148:149], 12, v[152:153]
	v_rcp_f32_e32 v154, v154
	v_rcp_f32_e32 v155, v155
	v_lshl_add_u64 v[148:149], s[66:67], 0, v[148:149]
	v_lshl_add_u64 v[148:149], v[148:149], 0, v[142:143]
	global_store_dwordx2 v[148:149], v[150:151], off nt
	v_lshlrev_b64 v[150:151], 11, v[152:153]
	v_mov_b32_e32 v250, v173
	v_mov_b32_e32 v252, v173
	v_lshl_add_u64 v[150:151], s[48:49], 0, v[150:151]
	v_mov_b32_dpp v250, v144 row_ror:1 row_mask:0xf bank_mask:0xf
	v_mov_b32_dpp v252, v145 row_ror:1 row_mask:0xf bank_mask:0xf
	v_mul_f32_e32 v154, v20, v154
	v_mul_f32_e32 v155, v21, v155
	v_cvt_pk_bf16_f32 v148, v156, v157
	v_cvt_pk_bf16_f32 v149, v154, v155
	v_lshl_add_u64 v[150:151], v[150:151], 0, v[142:143]
	global_store_dwordx2 v[150:151], v[148:149], off nt
	v_cndmask_b32_e64 v149, v252, v244, s[4:5]
	v_cndmask_b32_e64 v148, v250, v242, s[4:5]
	v_pk_mul_f32 v[140:141], v[140:141], v[148:149]
	v_cndmask_b32_e64 v153, v253, 0, s[6:7]
	v_cndmask_b32_e64 v152, v251, 0, s[6:7]
	v_pk_fma_f32 v[136:137], v[144:145], v[136:137], v[140:141]
	v_mov_b32_e32 v246, v173
	v_mov_b32_e32 v248, v173
	v_pk_fma_f32 v[132:133], v[132:133], v[152:153], v[136:137]
	v_mul_f32_e32 v136, 0xbfb8aa3b, v2
	v_mov_b32_dpp v246, v146 row_ror:1 row_mask:0xf bank_mask:0xf
	v_mov_b32_dpp v248, v147 row_ror:1 row_mask:0xf bank_mask:0xf
	v_exp_f32_e32 v136, v136
	v_mul_f32_e32 v137, 0xbfb8aa3b, v3
	v_cndmask_b32_e64 v151, v248, v240, s[4:5]
	v_cndmask_b32_e64 v150, v246, v238, s[4:5]
	v_exp_f32_e32 v137, v137
	v_pk_mul_f32 v[138:139], v[138:139], v[150:151]
	v_cndmask_b32_e64 v155, v249, 0, s[6:7]
	v_cndmask_b32_e64 v154, v247, 0, s[6:7]
	v_pk_fma_f32 v[134:135], v[146:147], v[134:135], v[138:139]
	v_pk_mul_f32 v[132:133], v[8:9], v[132:133]
	v_pk_fma_f32 v[130:131], v[130:131], v[154:155], v[134:135]
	v_add_f32_e32 v134, 1.0, v136
	v_rcp_f32_e32 v134, v134
	v_add_f32_e32 v135, 1.0, v137
	v_rcp_f32_e32 v135, v135
	v_mul_f32_e32 v136, 0xbfb8aa3b, v4
	v_mul_f32_e32 v137, 0xbfb8aa3b, v5
	v_exp_f32_e32 v136, v136
	v_exp_f32_e32 v137, v137
	v_mul_f32_e32 v138, v2, v134
	v_add_u32_e32 v134, 0xb0, v192
	v_mul_f32_e32 v139, v3, v135
	v_pk_mul_f32 v[130:131], v[6:7], v[130:131]
	v_ashrrev_i32_e32 v135, 31, v134
	v_cvt_pk_bf16_f32 v130, v130, v131
	v_cvt_pk_bf16_f32 v131, v132, v133
	v_lshlrev_b64 v[132:133], 12, v[134:135]
	v_add_f32_e32 v136, 1.0, v136
	v_add_f32_e32 v137, 1.0, v137
	v_lshl_add_u64 v[132:133], s[66:67], 0, v[132:133]
	v_rcp_f32_e32 v136, v136
	v_rcp_f32_e32 v137, v137
	v_lshl_add_u64 v[132:133], v[132:133], 0, v[142:143]
	global_store_dwordx2 v[132:133], v[130:131], off nt
	v_lshlrev_b64 v[132:133], 11, v[134:135]
	v_lshl_add_u64 v[132:133], s[48:49], 0, v[132:133]
	v_lshl_add_u64 v[132:133], v[132:133], 0, v[142:143]
	v_mul_f32_e32 v136, v4, v136
	v_mul_f32_e32 v137, v5, v137
	v_cvt_pk_bf16_f32 v130, v138, v139
	v_cvt_pk_bf16_f32 v131, v136, v137
	global_store_dwordx2 v[132:133], v[130:131], off nt
	s_cbranch_execnz .LBB0_260

; __device__ __forceinline__ unsigned cvt_pk_bf16(float lo, float hi) { unsigned r; asm volatile("v_cvt_pk_bf16_f32 %0, %1, %2" : "=v"(r) : "v"(lo), "v"(hi)); return r; }
;     __device__ __forceinline__ void operator()(const f32x4 (&acc)[2][2][4][2], const Unit& u, int wr, int wc, int fr, int fq) const {
;     ...
; #pragma unroll
;             for (int ai = 0; ai < 2; ++ai)
; #pragma unroll
;                 for (int m = 0; m < 4; ++m) {
;                     const int r = row0 + ai * HALF + m * 16;
;                     const f32x4 cs = colh ? csA[m] : csA[ai], sn = colh ? snA[m] : snA[ai];
;                     bf16_t* rowp = P + (size_t)r * ldp + col0;
; #pragma unroll
;                     for (int bj = 0; bj < 2; ++bj) {
;                         const f32x4 v0 = acc[ai][bj][m][0], v1 = acc[ai][bj][m][1]; f32x4 o0, o1;
;                         o0[0] = v0[0] * cs[0] - v0[1] * sn[0]; o0[1] = v0[0] * sn[0] + v0[1] * cs[0];
;                         o0[2] = v0[2] * cs[1] - v0[3] * sn[1]; o0[3] = v0[2] * sn[1] + v0[3] * cs[1];
;                         o1[0] = v1[0] * cs[2] - v1[1] * sn[2]; o1[1] = v1[0] * sn[2] + v1[1] * cs[2];
;                         o1[2] = v1[2] * cs[3] - v1[3] * sn[3]; o1[3] = v1[2] * sn[3] + v1[3] * cs[3];
;                         o0 = o0 * s; o1 = o1 * s;
;                         u32x4 w; w.x = cvt_pk_bf16(o0[0], o0[1]); w.y = cvt_pk_bf16(o0[2], o0[3]); w.z = cvt_pk_bf16(o1[0], o1[1]); w.w = cvt_pk_bf16(o1[2], o1[3]);
;                         *(u32x4*)(rowp + bj * HALF) = w; }
;                 }
.LBB0_268:
	s_waitcnt vmcnt(0)
	v_pk_mul_f32 v[230:231], v[126:127], v[154:155] op_sel_hi:[1,0]
	v_mov_b32_e32 v234, v159
	v_pk_fma_f32 v[232:233], v[126:127], v[158:159], v[230:231] op_sel:[0,0,1] op_sel_hi:[1,0,0] neg_lo:[0,0,1] neg_hi:[0,0,1]
	v_pk_fma_f32 v[126:127], v[126:127], v[158:159], v[230:231] op_sel:[0,0,1] op_sel_hi:[1,0,0]
	s_add_i32 s12, s52, -8
	v_mov_b32_e32 v126, v155
	v_pk_mul_f32 v[230:231], v[128:129], v[126:127] op_sel_hi:[1,0]
	v_lshl_or_b32 v206, s52, 8, v224
	v_pk_fma_f32 v[236:237], v[128:129], v[234:235], v[230:231] op_sel:[0,0,1] op_sel_hi:[1,0,0] neg_lo:[0,0,1] neg_hi:[0,0,1]
	v_pk_fma_f32 v[128:129], v[128:129], v[234:235], v[230:231] op_sel:[0,0,1] op_sel_hi:[1,0,0]
	s_cmp_lt_u32 s12, -4
	v_pk_mul_f32 v[230:231], v[122:123], v[156:157] op_sel_hi:[1,0]
	v_mov_b32_e32 v128, v157
	s_cselect_b64 s[12:13], -1, 0
	v_ashrrev_i32_e32 v207, 31, v206
	v_mov_b64_e32 v[204:205], s[38:39]
	v_pk_fma_f32 v[238:239], v[122:123], v[160:161], v[230:231] op_sel:[0,0,1] op_sel_hi:[1,0,0] neg_lo:[0,0,1] neg_hi:[0,0,1]
	v_pk_fma_f32 v[122:123], v[122:123], v[160:161], v[230:231] op_sel:[0,0,1] op_sel_hi:[1,0,0]
	v_pk_mul_f32 v[230:231], v[124:125], v[128:129] op_sel_hi:[1,0]
	v_mov_b32_e32 v240, v161
	v_cndmask_b32_e64 v172, v228, 1.0, s[12:13]
	v_mad_i64_i32 v[212:213], s[12:13], v192, s44, v[204:205]
	v_lshlrev_b64 v[206:207], 1, v[206:207]
	v_pk_fma_f32 v[242:243], v[124:125], v[240:241], v[230:231] op_sel:[0,0,1] op_sel_hi:[1,0,0] neg_lo:[0,0,1] neg_hi:[0,0,1]
	v_pk_fma_f32 v[124:125], v[124:125], v[240:241], v[230:231] op_sel:[0,0,1] op_sel_hi:[1,0,0]
	v_mov_b32_e32 v237, v129
	v_mov_b32_e32 v233, v127
	v_mov_b32_e32 v239, v123
	v_lshl_add_u64 v[212:213], v[212:213], 0, v[206:207]
	v_pk_mul_f32 v[230:231], v[172:173], v[236:237] op_sel_hi:[0,1]
	v_pk_mul_f32 v[232:233], v[172:173], v[232:233] op_sel_hi:[0,1]
	v_mov_b32_e32 v243, v125
	v_pk_mul_f32 v[124:125], v[172:173], v[238:239] op_sel_hi:[0,1]
	v_cvt_pk_bf16_f32 v122, v232, v233
	v_cvt_pk_bf16_f32 v123, v230, v231
	v_pk_mul_f32 v[236:237], v[172:173], v[242:243] op_sel_hi:[0,1]
	v_cvt_pk_bf16_f32 v124, v124, v125
	v_cvt_pk_bf16_f32 v125, v236, v237
	global_store_dwordx4 v[212:213], v[122:125], off nt
	v_mad_i64_i32 v[202:203], s[12:13], v202, s44, v[204:205]
	s_nop 0
	v_pk_mul_f32 v[122:123], v[118:119], v[154:155] op_sel_hi:[1,0]
	v_lshl_add_u64 v[202:203], v[202:203], 0, v[206:207]
	v_pk_fma_f32 v[124:125], v[118:119], v[158:159], v[122:123] op_sel:[0,0,1] op_sel_hi:[1,0,0] neg_lo:[0,0,1] neg_hi:[0,0,1]
	v_pk_fma_f32 v[118:119], v[118:119], v[158:159], v[122:123] op_sel:[0,0,1] op_sel_hi:[1,0,0]
	v_pk_mul_f32 v[122:123], v[120:121], v[126:127] op_sel_hi:[1,0]
	v_mov_b32_e32 v125, v119
	v_pk_fma_f32 v[126:127], v[120:121], v[234:235], v[122:123] op_sel:[0,0,1] op_sel_hi:[1,0,0] neg_lo:[0,0,1] neg_hi:[0,0,1]
	v_pk_fma_f32 v[120:121], v[120:121], v[234:235], v[122:123] op_sel:[0,0,1] op_sel_hi:[1,0,0]
	v_pk_mul_f32 v[122:123], v[114:115], v[156:157] op_sel_hi:[1,0]
	v_mov_b32_e32 v127, v121
	v_pk_fma_f32 v[230:231], v[114:115], v[160:161], v[122:123] op_sel:[0,0,1] op_sel_hi:[1,0,0] neg_lo:[0,0,1] neg_hi:[0,0,1]
	v_pk_fma_f32 v[114:115], v[114:115], v[160:161], v[122:123] op_sel:[0,0,1] op_sel_hi:[1,0,0]
	v_pk_mul_f32 v[122:123], v[116:117], v[128:129] op_sel_hi:[1,0]
	v_mov_b32_e32 v231, v115
	v_pk_fma_f32 v[128:129], v[116:117], v[240:241], v[122:123] op_sel:[0,0,1] op_sel_hi:[1,0,0] neg_lo:[0,0,1] neg_hi:[0,0,1]
	v_pk_fma_f32 v[116:117], v[116:117], v[240:241], v[122:123] op_sel:[0,0,1] op_sel_hi:[1,0,0]
	v_pk_mul_f32 v[120:121], v[172:173], v[126:127] op_sel_hi:[0,1]
	v_mov_b32_e32 v129, v117
	v_pk_mul_f32 v[122:123], v[172:173], v[128:129] op_sel_hi:[0,1]
	v_pk_mul_f32 v[116:117], v[172:173], v[230:231] op_sel_hi:[0,1]
	v_cndmask_b32_e64 v128, v154, v138, s[8:9]
	v_pk_mul_f32 v[118:119], v[172:173], v[124:125] op_sel_hi:[0,1]
	v_cvt_pk_bf16_f32 v114, v118, v119
	v_cvt_pk_bf16_f32 v115, v120, v121
	v_cvt_pk_bf16_f32 v116, v116, v117
	v_cvt_pk_bf16_f32 v117, v122, v123
	global_store_dwordx4 v[212:213], v[114:117], off offset:256 nt
	v_cndmask_b32_e64 v120, v158, v142, s[8:9]
	v_cndmask_b32_e64 v126, v155, v139, s[8:9]
	v_pk_mul_f32 v[212:213], v[110:111], v[128:129] op_sel_hi:[1,0]
	v_cndmask_b32_e64 v118, v159, v143, s[8:9]
	v_cndmask_b32_e64 v124, v156, v140, s[8:9]
	v_pk_fma_f32 v[230:231], v[110:111], v[120:121], v[212:213] op_sel:[0,0,1] op_sel_hi:[1,0,0] neg_lo:[0,0,1] neg_hi:[0,0,1]
	v_pk_fma_f32 v[110:111], v[110:111], v[120:121], v[212:213] op_sel:[0,0,1] op_sel_hi:[1,0,0]
	v_pk_mul_f32 v[212:213], v[112:113], v[126:127] op_sel_hi:[1,0]
	v_cndmask_b32_e64 v116, v160, v144, s[8:9]
	v_cndmask_b32_e64 v122, v157, v141, s[8:9]
	v_pk_fma_f32 v[232:233], v[112:113], v[118:119], v[212:213] op_sel:[0,0,1] op_sel_hi:[1,0,0] neg_lo:[0,0,1] neg_hi:[0,0,1]
	v_pk_fma_f32 v[112:113], v[112:113], v[118:119], v[212:213] op_sel:[0,0,1] op_sel_hi:[1,0,0]
	v_pk_mul_f32 v[212:213], v[106:107], v[124:125] op_sel_hi:[1,0]
	v_cndmask_b32_e64 v114, v161, v145, s[8:9]
	v_pk_fma_f32 v[234:235], v[106:107], v[116:117], v[212:213] op_sel:[0,0,1] op_sel_hi:[1,0,0] neg_lo:[0,0,1] neg_hi:[0,0,1]
	v_pk_fma_f32 v[106:107], v[106:107], v[116:117], v[212:213] op_sel:[0,0,1] op_sel_hi:[1,0,0]
	v_pk_mul_f32 v[212:213], v[108:109], v[122:123] op_sel_hi:[1,0]
	v_mov_b32_e32 v233, v113
	v_pk_fma_f32 v[236:237], v[108:109], v[114:115], v[212:213] op_sel:[0,0,1] op_sel_hi:[1,0,0] neg_lo:[0,0,1] neg_hi:[0,0,1]
	v_pk_fma_f32 v[108:109], v[108:109], v[114:115], v[212:213] op_sel:[0,0,1] op_sel_hi:[1,0,0]
	v_mov_b32_e32 v231, v111
	v_mov_b32_e32 v235, v107
	v_pk_mul_f32 v[112:113], v[172:173], v[232:233] op_sel_hi:[0,1]
; __device__ __forceinline__ unsigned cvt_pk_bf16(float lo, float hi) { unsigned r; asm volatile("v_cvt_pk_bf16_f32 %0, %1, %2" : "=v"(r) : "v"(lo), "v"(hi)); return r; }
;     __device__ __forceinline__ void operator()(const f32x4 (&acc)[2][2][4][2], const Unit& u, int wr, int wc, int fr, int fq) const {
;     ...
; #pragma unroll
;             for (int ai = 0; ai < 2; ++ai)
; #pragma unroll
;                 for (int m = 0; m < 4; ++m) {
;                     const int r = row0 + ai * HALF + m * 16;
;                     const f32x4 cs = colh ? csA[m] : csA[ai], sn = colh ? snA[m] : snA[ai];
;                     bf16_t* rowp = P + (size_t)r * ldp + col0;
; #pragma unroll
;                     for (int bj = 0; bj < 2; ++bj) {
;                         const f32x4 v0 = acc[ai][bj][m][0], v1 = acc[ai][bj][m][1]; f32x4 o0, o1;
;                         o0[0] = v0[0] * cs[0] - v0[1] * sn[0]; o0[1] = v0[0] * sn[0] + v0[1] * cs[0];
;                         o0[2] = v0[2] * cs[1] - v0[3] * sn[1]; o0[3] = v0[2] * sn[1] + v0[3] * cs[1];
;                         o1[0] = v1[0] * cs[2] - v1[1] * sn[2]; o1[1] = v1[0] * sn[2] + v1[1] * cs[2];
;                         o1[2] = v1[2] * cs[3] - v1[3] * sn[3]; o1[3] = v1[2] * sn[3] + v1[3] * cs[3];
;                         o0 = o0 * s; o1 = o1 * s;
;                         u32x4 w; w.x = cvt_pk_bf16(o0[0], o0[1]); w.y = cvt_pk_bf16(o0[2], o0[3]); w.z = cvt_pk_bf16(o1[0], o1[1]); w.w = cvt_pk_bf16(o1[2], o1[3]);
;                         *(u32x4*)(rowp + bj * HALF) = w; }
;                 }
	v_pk_mul_f32 v[110:111], v[172:173], v[230:231] op_sel_hi:[0,1]
	v_mov_b32_e32 v237, v109
	v_pk_mul_f32 v[108:109], v[172:173], v[234:235] op_sel_hi:[0,1]
	v_cvt_pk_bf16_f32 v106, v110, v111
	v_cvt_pk_bf16_f32 v107, v112, v113
	v_pk_mul_f32 v[212:213], v[172:173], v[236:237] op_sel_hi:[0,1]
	v_cvt_pk_bf16_f32 v108, v108, v109
	v_cvt_pk_bf16_f32 v109, v212, v213
	global_store_dwordx4 v[202:203], v[106:109], off nt
	s_nop 1
	v_pk_mul_f32 v[106:107], v[102:103], v[128:129] op_sel_hi:[1,0]
	s_nop 0
	v_pk_fma_f32 v[108:109], v[102:103], v[120:121], v[106:107] op_sel:[0,0,1] op_sel_hi:[1,0,0] neg_lo:[0,0,1] neg_hi:[0,0,1]
	v_pk_fma_f32 v[102:103], v[102:103], v[120:121], v[106:107] op_sel:[0,0,1] op_sel_hi:[1,0,0]
	v_pk_mul_f32 v[106:107], v[104:105], v[126:127] op_sel_hi:[1,0]
	v_mov_b32_e32 v109, v103
	v_pk_fma_f32 v[110:111], v[104:105], v[118:119], v[106:107] op_sel:[0,0,1] op_sel_hi:[1,0,0] neg_lo:[0,0,1] neg_hi:[0,0,1]
	v_pk_fma_f32 v[104:105], v[104:105], v[118:119], v[106:107] op_sel:[0,0,1] op_sel_hi:[1,0,0]
	v_pk_mul_f32 v[106:107], v[98:99], v[124:125] op_sel_hi:[1,0]
	v_mov_b32_e32 v111, v105
	v_pk_fma_f32 v[112:113], v[98:99], v[116:117], v[106:107] op_sel:[0,0,1] op_sel_hi:[1,0,0] neg_lo:[0,0,1] neg_hi:[0,0,1]
	v_pk_fma_f32 v[98:99], v[98:99], v[116:117], v[106:107] op_sel:[0,0,1] op_sel_hi:[1,0,0]
	v_pk_mul_f32 v[106:107], v[100:101], v[122:123] op_sel_hi:[1,0]
	v_mov_b32_e32 v113, v99
	v_pk_fma_f32 v[116:117], v[100:101], v[114:115], v[106:107] op_sel:[0,0,1] op_sel_hi:[1,0,0] neg_lo:[0,0,1] neg_hi:[0,0,1]
	v_pk_fma_f32 v[100:101], v[100:101], v[114:115], v[106:107] op_sel:[0,0,1] op_sel_hi:[1,0,0]
	v_pk_mul_f32 v[104:105], v[172:173], v[110:111] op_sel_hi:[0,1]
	v_mov_b32_e32 v117, v101
	v_pk_mul_f32 v[100:101], v[172:173], v[112:113] op_sel_hi:[0,1]
	v_cndmask_b32_e64 v112, v154, v146, s[8:9]
	v_pk_mul_f32 v[102:103], v[172:173], v[108:109] op_sel_hi:[0,1]
	v_pk_mul_f32 v[106:107], v[172:173], v[116:117] op_sel_hi:[0,1]
	v_cvt_pk_bf16_f32 v98, v102, v103
	v_cvt_pk_bf16_f32 v99, v104, v105
	v_cndmask_b32_e64 v104, v158, v150, s[8:9]
	v_cndmask_b32_e64 v110, v155, v147, s[8:9]
	v_pk_mul_f32 v[116:117], v[94:95], v[112:113] op_sel_hi:[1,0]
	v_cvt_pk_bf16_f32 v100, v100, v101
	v_cndmask_b32_e64 v102, v159, v151, s[8:9]
	v_cndmask_b32_e64 v108, v156, v148, s[8:9]
	v_pk_fma_f32 v[118:119], v[94:95], v[104:105], v[116:117] op_sel:[0,0,1] op_sel_hi:[1,0,0] neg_lo:[0,0,1] neg_hi:[0,0,1]
	v_pk_fma_f32 v[94:95], v[94:95], v[104:105], v[116:117] op_sel:[0,0,1] op_sel_hi:[1,0,0]
	v_pk_mul_f32 v[116:117], v[96:97], v[110:111] op_sel_hi:[1,0]
	v_cvt_pk_bf16_f32 v101, v106, v107
	global_store_dwordx4 v[202:203], v[98:101], off offset:256 nt
	v_cndmask_b32_e64 v106, v157, v149, s[8:9]
	v_pk_fma_f32 v[120:121], v[96:97], v[102:103], v[116:117] op_sel:[0,0,1] op_sel_hi:[1,0,0] neg_lo:[0,0,1] neg_hi:[0,0,1]
	v_cndmask_b32_e64 v100, v160, v152, s[8:9]
	v_pk_fma_f32 v[96:97], v[96:97], v[102:103], v[116:117] op_sel:[0,0,1] op_sel_hi:[1,0,0]
	v_pk_mul_f32 v[116:117], v[90:91], v[108:109] op_sel_hi:[1,0]
	v_cndmask_b32_e64 v98, v161, v153, s[8:9]
	v_pk_fma_f32 v[122:123], v[90:91], v[100:101], v[116:117] op_sel:[0,0,1] op_sel_hi:[1,0,0] neg_lo:[0,0,1] neg_hi:[0,0,1]
	v_pk_fma_f32 v[90:91], v[90:91], v[100:101], v[116:117] op_sel:[0,0,1] op_sel_hi:[1,0,0]
	v_pk_mul_f32 v[116:117], v[92:93], v[106:107] op_sel_hi:[1,0]
	v_mad_i64_i32 v[114:115], s[12:13], v200, s44, v[204:205]
	v_pk_fma_f32 v[124:125], v[92:93], v[98:99], v[116:117] op_sel:[0,0,1] op_sel_hi:[1,0,0] neg_lo:[0,0,1] neg_hi:[0,0,1]
	v_pk_fma_f32 v[92:93], v[92:93], v[98:99], v[116:117] op_sel:[0,0,1] op_sel_hi:[1,0,0]
	v_mov_b32_e32 v121, v97
	v_mov_b32_e32 v119, v95
	v_mov_b32_e32 v123, v91
	v_lshl_add_u64 v[114:115], v[114:115], 0, v[206:207]
	v_pk_mul_f32 v[96:97], v[172:173], v[120:121] op_sel_hi:[0,1]
	v_pk_mul_f32 v[94:95], v[172:173], v[118:119] op_sel_hi:[0,1]
	v_mov_b32_e32 v125, v93
	v_pk_mul_f32 v[92:93], v[172:173], v[122:123] op_sel_hi:[0,1]
	v_cvt_pk_bf16_f32 v90, v94, v95
	v_cvt_pk_bf16_f32 v91, v96, v97
	v_pk_mul_f32 v[116:117], v[172:173], v[124:125] op_sel_hi:[0,1]
	v_cvt_pk_bf16_f32 v92, v92, v93
	v_cvt_pk_bf16_f32 v93, v116, v117
	global_store_dwordx4 v[114:115], v[90:93], off nt
	s_nop 1
	v_pk_mul_f32 v[90:91], v[86:87], v[112:113] op_sel_hi:[1,0]
	s_nop 0
	v_pk_fma_f32 v[92:93], v[86:87], v[104:105], v[90:91] op_sel:[0,0,1] op_sel_hi:[1,0,0] neg_lo:[0,0,1] neg_hi:[0,0,1]
	v_pk_fma_f32 v[86:87], v[86:87], v[104:105], v[90:91] op_sel:[0,0,1] op_sel_hi:[1,0,0]
	v_pk_mul_f32 v[90:91], v[88:89], v[110:111] op_sel_hi:[1,0]
	v_mov_b32_e32 v93, v87
	v_pk_fma_f32 v[94:95], v[88:89], v[102:103], v[90:91] op_sel:[0,0,1] op_sel_hi:[1,0,0] neg_lo:[0,0,1] neg_hi:[0,0,1]
	v_pk_fma_f32 v[88:89], v[88:89], v[102:103], v[90:91] op_sel:[0,0,1] op_sel_hi:[1,0,0]
	v_pk_mul_f32 v[90:91], v[82:83], v[108:109] op_sel_hi:[1,0]
	v_mov_b32_e32 v95, v89
	v_pk_fma_f32 v[96:97], v[82:83], v[100:101], v[90:91] op_sel:[0,0,1] op_sel_hi:[1,0,0] neg_lo:[0,0,1] neg_hi:[0,0,1]
	v_pk_fma_f32 v[82:83], v[82:83], v[100:101], v[90:91] op_sel:[0,0,1] op_sel_hi:[1,0,0]
	v_pk_mul_f32 v[90:91], v[84:85], v[106:107] op_sel_hi:[1,0]
	v_mov_b32_e32 v97, v83
	v_pk_fma_f32 v[100:101], v[84:85], v[98:99], v[90:91] op_sel:[0,0,1] op_sel_hi:[1,0,0] neg_lo:[0,0,1] neg_hi:[0,0,1]
	v_pk_fma_f32 v[84:85], v[84:85], v[98:99], v[90:91] op_sel:[0,0,1] op_sel_hi:[1,0,0]
	v_pk_mul_f32 v[88:89], v[172:173], v[94:95] op_sel_hi:[0,1]
	v_mov_b32_e32 v101, v85
	v_pk_mul_f32 v[84:85], v[172:173], v[96:97] op_sel_hi:[0,1]
	v_cndmask_b32_e64 v96, v154, v130, s[8:9]
	v_pk_mul_f32 v[86:87], v[172:173], v[92:93] op_sel_hi:[0,1]
; __device__ __forceinline__ unsigned cvt_pk_bf16(float lo, float hi) { unsigned r; asm volatile("v_cvt_pk_bf16_f32 %0, %1, %2" : "=v"(r) : "v"(lo), "v"(hi)); return r; }
;     __device__ __forceinline__ void operator()(const f32x4 (&acc)[2][2][4][2], const Unit& u, int wr, int wc, int fr, int fq) const {
;     ...
; #pragma unroll
;             for (int ai = 0; ai < 2; ++ai)
; #pragma unroll
;                 for (int m = 0; m < 4; ++m) {
;                     const int r = row0 + ai * HALF + m * 16;
;                     const f32x4 cs = colh ? csA[m] : csA[ai], sn = colh ? snA[m] : snA[ai];
;                     bf16_t* rowp = P + (size_t)r * ldp + col0;
; #pragma unroll
;                     for (int bj = 0; bj < 2; ++bj) {
;                         const f32x4 v0 = acc[ai][bj][m][0], v1 = acc[ai][bj][m][1]; f32x4 o0, o1;
;                         o0[0] = v0[0] * cs[0] - v0[1] * sn[0]; o0[1] = v0[0] * sn[0] + v0[1] * cs[0];
;                         o0[2] = v0[2] * cs[1] - v0[3] * sn[1]; o0[3] = v0[2] * sn[1] + v0[3] * cs[1];
;                         o1[0] = v1[0] * cs[2] - v1[1] * sn[2]; o1[1] = v1[0] * sn[2] + v1[1] * cs[2];
;                         o1[2] = v1[2] * cs[3] - v1[3] * sn[3]; o1[3] = v1[2] * sn[3] + v1[3] * cs[3];
;                         o0 = o0 * s; o1 = o1 * s;
;                         u32x4 w; w.x = cvt_pk_bf16(o0[0], o0[1]); w.y = cvt_pk_bf16(o0[2], o0[3]); w.z = cvt_pk_bf16(o1[0], o1[1]); w.w = cvt_pk_bf16(o1[2], o1[3]);
;                         *(u32x4*)(rowp + bj * HALF) = w; }
;                 }
	v_pk_mul_f32 v[90:91], v[172:173], v[100:101] op_sel_hi:[0,1]
	v_cvt_pk_bf16_f32 v82, v86, v87
	v_cvt_pk_bf16_f32 v83, v88, v89
	v_cndmask_b32_e64 v88, v158, v134, s[8:9]
	v_cndmask_b32_e64 v94, v155, v131, s[8:9]
	v_pk_mul_f32 v[100:101], v[78:79], v[96:97] op_sel_hi:[1,0]
	v_cvt_pk_bf16_f32 v84, v84, v85
	v_cndmask_b32_e64 v86, v159, v135, s[8:9]
	v_cndmask_b32_e64 v92, v156, v132, s[8:9]
	v_pk_fma_f32 v[102:103], v[78:79], v[88:89], v[100:101] op_sel:[0,0,1] op_sel_hi:[1,0,0] neg_lo:[0,0,1] neg_hi:[0,0,1]
	v_pk_fma_f32 v[78:79], v[78:79], v[88:89], v[100:101] op_sel:[0,0,1] op_sel_hi:[1,0,0]
	v_pk_mul_f32 v[100:101], v[80:81], v[94:95] op_sel_hi:[1,0]
	v_cvt_pk_bf16_f32 v85, v90, v91
	global_store_dwordx4 v[114:115], v[82:85], off offset:256 nt
	v_cndmask_b32_e64 v90, v157, v133, s[8:9]
	v_pk_fma_f32 v[104:105], v[80:81], v[86:87], v[100:101] op_sel:[0,0,1] op_sel_hi:[1,0,0] neg_lo:[0,0,1] neg_hi:[0,0,1]
	v_cndmask_b32_e64 v84, v160, v136, s[8:9]
	v_pk_fma_f32 v[80:81], v[80:81], v[86:87], v[100:101] op_sel:[0,0,1] op_sel_hi:[1,0,0]
	v_pk_mul_f32 v[100:101], v[74:75], v[92:93] op_sel_hi:[1,0]
	v_cndmask_b32_e64 v82, v161, v137, s[8:9]
	v_pk_fma_f32 v[106:107], v[74:75], v[84:85], v[100:101] op_sel:[0,0,1] op_sel_hi:[1,0,0] neg_lo:[0,0,1] neg_hi:[0,0,1]
	v_pk_fma_f32 v[74:75], v[74:75], v[84:85], v[100:101] op_sel:[0,0,1] op_sel_hi:[1,0,0]
	v_pk_mul_f32 v[100:101], v[76:77], v[90:91] op_sel_hi:[1,0]
	v_mad_i64_i32 v[98:99], s[12:13], v198, s44, v[204:205]
	v_pk_fma_f32 v[108:109], v[76:77], v[82:83], v[100:101] op_sel:[0,0,1] op_sel_hi:[1,0,0] neg_lo:[0,0,1] neg_hi:[0,0,1]
	v_pk_fma_f32 v[76:77], v[76:77], v[82:83], v[100:101] op_sel:[0,0,1] op_sel_hi:[1,0,0]
	v_mov_b32_e32 v105, v81
	v_mov_b32_e32 v103, v79
	v_mov_b32_e32 v107, v75
	v_lshl_add_u64 v[98:99], v[98:99], 0, v[206:207]
	v_pk_mul_f32 v[80:81], v[172:173], v[104:105] op_sel_hi:[0,1]
	v_pk_mul_f32 v[78:79], v[172:173], v[102:103] op_sel_hi:[0,1]
	v_mov_b32_e32 v109, v77
	v_pk_mul_f32 v[76:77], v[172:173], v[106:107] op_sel_hi:[0,1]
	v_cvt_pk_bf16_f32 v74, v78, v79
	v_cvt_pk_bf16_f32 v75, v80, v81
	v_pk_mul_f32 v[100:101], v[172:173], v[108:109] op_sel_hi:[0,1]
	v_cvt_pk_bf16_f32 v76, v76, v77
	v_cvt_pk_bf16_f32 v77, v100, v101
	global_store_dwordx4 v[98:99], v[74:77], off nt
	s_nop 1
	v_pk_mul_f32 v[74:75], v[70:71], v[96:97] op_sel_hi:[1,0]
	s_nop 0
	v_pk_fma_f32 v[76:77], v[70:71], v[88:89], v[74:75] op_sel:[0,0,1] op_sel_hi:[1,0,0] neg_lo:[0,0,1] neg_hi:[0,0,1]
	v_pk_fma_f32 v[70:71], v[70:71], v[88:89], v[74:75] op_sel:[0,0,1] op_sel_hi:[1,0,0]
	v_pk_mul_f32 v[74:75], v[72:73], v[94:95] op_sel_hi:[1,0]
	v_mov_b32_e32 v77, v71
	v_pk_fma_f32 v[78:79], v[72:73], v[86:87], v[74:75] op_sel:[0,0,1] op_sel_hi:[1,0,0] neg_lo:[0,0,1] neg_hi:[0,0,1]
	v_pk_fma_f32 v[72:73], v[72:73], v[86:87], v[74:75] op_sel:[0,0,1] op_sel_hi:[1,0,0]
	v_pk_mul_f32 v[74:75], v[66:67], v[92:93] op_sel_hi:[1,0]
	v_mov_b32_e32 v79, v73
	v_pk_fma_f32 v[80:81], v[66:67], v[84:85], v[74:75] op_sel:[0,0,1] op_sel_hi:[1,0,0] neg_lo:[0,0,1] neg_hi:[0,0,1]
	v_pk_fma_f32 v[66:67], v[66:67], v[84:85], v[74:75] op_sel:[0,0,1] op_sel_hi:[1,0,0]
	v_pk_mul_f32 v[74:75], v[68:69], v[90:91] op_sel_hi:[1,0]
	v_mov_b32_e32 v81, v67
	v_pk_fma_f32 v[84:85], v[68:69], v[82:83], v[74:75] op_sel:[0,0,1] op_sel_hi:[1,0,0] neg_lo:[0,0,1] neg_hi:[0,0,1]
	v_pk_fma_f32 v[68:69], v[68:69], v[82:83], v[74:75] op_sel:[0,0,1] op_sel_hi:[1,0,0]
	v_pk_mul_f32 v[72:73], v[172:173], v[78:79] op_sel_hi:[0,1]
	v_mov_b32_e32 v85, v69
	v_pk_mul_f32 v[68:69], v[172:173], v[80:81] op_sel_hi:[0,1]
	v_cndmask_b32_e64 v80, v138, v154, s[8:9]
	v_pk_mul_f32 v[70:71], v[172:173], v[76:77] op_sel_hi:[0,1]
	v_pk_mul_f32 v[74:75], v[172:173], v[84:85] op_sel_hi:[0,1]
	v_cvt_pk_bf16_f32 v66, v70, v71
	v_cvt_pk_bf16_f32 v67, v72, v73
	v_cndmask_b32_e64 v72, v142, v158, s[8:9]
	v_cndmask_b32_e64 v78, v139, v155, s[8:9]
	v_pk_mul_f32 v[84:85], v[62:63], v[80:81] op_sel_hi:[1,0]
	v_cvt_pk_bf16_f32 v68, v68, v69
	v_cndmask_b32_e64 v70, v143, v159, s[8:9]
	v_cndmask_b32_e64 v76, v140, v156, s[8:9]
	v_pk_fma_f32 v[86:87], v[62:63], v[72:73], v[84:85] op_sel:[0,0,1] op_sel_hi:[1,0,0] neg_lo:[0,0,1] neg_hi:[0,0,1]
	v_pk_fma_f32 v[62:63], v[62:63], v[72:73], v[84:85] op_sel:[0,0,1] op_sel_hi:[1,0,0]
	v_pk_mul_f32 v[84:85], v[64:65], v[78:79] op_sel_hi:[1,0]
	v_cvt_pk_bf16_f32 v69, v74, v75
	global_store_dwordx4 v[98:99], v[66:69], off offset:256 nt
	v_cndmask_b32_e64 v74, v141, v157, s[8:9]
	v_pk_fma_f32 v[88:89], v[64:65], v[70:71], v[84:85] op_sel:[0,0,1] op_sel_hi:[1,0,0] neg_lo:[0,0,1] neg_hi:[0,0,1]
	v_cndmask_b32_e64 v68, v144, v160, s[8:9]
	v_pk_fma_f32 v[64:65], v[64:65], v[70:71], v[84:85] op_sel:[0,0,1] op_sel_hi:[1,0,0]
	v_pk_mul_f32 v[84:85], v[58:59], v[76:77] op_sel_hi:[1,0]
	v_cndmask_b32_e64 v66, v145, v161, s[8:9]
	v_pk_fma_f32 v[90:91], v[58:59], v[68:69], v[84:85] op_sel:[0,0,1] op_sel_hi:[1,0,0] neg_lo:[0,0,1] neg_hi:[0,0,1]
	v_pk_fma_f32 v[58:59], v[58:59], v[68:69], v[84:85] op_sel:[0,0,1] op_sel_hi:[1,0,0]
	v_pk_mul_f32 v[84:85], v[60:61], v[74:75] op_sel_hi:[1,0]
	v_mad_i64_i32 v[82:83], s[12:13], v196, s44, v[204:205]
	v_pk_fma_f32 v[92:93], v[60:61], v[66:67], v[84:85] op_sel:[0,0,1] op_sel_hi:[1,0,0] neg_lo:[0,0,1] neg_hi:[0,0,1]
	v_pk_fma_f32 v[60:61], v[60:61], v[66:67], v[84:85] op_sel:[0,0,1] op_sel_hi:[1,0,0]
	v_mov_b32_e32 v89, v65
	v_mov_b32_e32 v87, v63
	v_mov_b32_e32 v91, v59
	v_lshl_add_u64 v[82:83], v[82:83], 0, v[206:207]
	v_pk_mul_f32 v[64:65], v[172:173], v[88:89] op_sel_hi:[0,1]
	v_pk_mul_f32 v[62:63], v[172:173], v[86:87] op_sel_hi:[0,1]
	v_mov_b32_e32 v93, v61
	v_pk_mul_f32 v[60:61], v[172:173], v[90:91] op_sel_hi:[0,1]
; __device__ __forceinline__ unsigned cvt_pk_bf16(float lo, float hi) { unsigned r; asm volatile("v_cvt_pk_bf16_f32 %0, %1, %2" : "=v"(r) : "v"(lo), "v"(hi)); return r; }
;     __device__ __forceinline__ void operator()(const f32x4 (&acc)[2][2][4][2], const Unit& u, int wr, int wc, int fr, int fq) const {
;     ...
; #pragma unroll
;             for (int ai = 0; ai < 2; ++ai)
; #pragma unroll
;                 for (int m = 0; m < 4; ++m) {
;                     const int r = row0 + ai * HALF + m * 16;
;                     const f32x4 cs = colh ? csA[m] : csA[ai], sn = colh ? snA[m] : snA[ai];
;                     bf16_t* rowp = P + (size_t)r * ldp + col0;
; #pragma unroll
;                     for (int bj = 0; bj < 2; ++bj) {
;                         const f32x4 v0 = acc[ai][bj][m][0], v1 = acc[ai][bj][m][1]; f32x4 o0, o1;
;                         o0[0] = v0[0] * cs[0] - v0[1] * sn[0]; o0[1] = v0[0] * sn[0] + v0[1] * cs[0];
;                         o0[2] = v0[2] * cs[1] - v0[3] * sn[1]; o0[3] = v0[2] * sn[1] + v0[3] * cs[1];
;                         o1[0] = v1[0] * cs[2] - v1[1] * sn[2]; o1[1] = v1[0] * sn[2] + v1[1] * cs[2];
;                         o1[2] = v1[2] * cs[3] - v1[3] * sn[3]; o1[3] = v1[2] * sn[3] + v1[3] * cs[3];
;                         o0 = o0 * s; o1 = o1 * s;
;                         u32x4 w; w.x = cvt_pk_bf16(o0[0], o0[1]); w.y = cvt_pk_bf16(o0[2], o0[3]); w.z = cvt_pk_bf16(o1[0], o1[1]); w.w = cvt_pk_bf16(o1[2], o1[3]);
;                         *(u32x4*)(rowp + bj * HALF) = w; }
;                 }
	v_cvt_pk_bf16_f32 v58, v62, v63
	v_cvt_pk_bf16_f32 v59, v64, v65
	v_pk_mul_f32 v[84:85], v[172:173], v[92:93] op_sel_hi:[0,1]
	v_cvt_pk_bf16_f32 v60, v60, v61
	v_cvt_pk_bf16_f32 v61, v84, v85
	global_store_dwordx4 v[82:83], v[58:61], off nt
	s_nop 1
	v_pk_mul_f32 v[58:59], v[54:55], v[80:81] op_sel_hi:[1,0]
	s_nop 0
	v_pk_fma_f32 v[60:61], v[54:55], v[72:73], v[58:59] op_sel:[0,0,1] op_sel_hi:[1,0,0] neg_lo:[0,0,1] neg_hi:[0,0,1]
	v_pk_fma_f32 v[54:55], v[54:55], v[72:73], v[58:59] op_sel:[0,0,1] op_sel_hi:[1,0,0]
	v_pk_mul_f32 v[58:59], v[56:57], v[78:79] op_sel_hi:[1,0]
	v_mov_b32_e32 v61, v55
	v_pk_fma_f32 v[62:63], v[56:57], v[70:71], v[58:59] op_sel:[0,0,1] op_sel_hi:[1,0,0] neg_lo:[0,0,1] neg_hi:[0,0,1]
	v_pk_fma_f32 v[56:57], v[56:57], v[70:71], v[58:59] op_sel:[0,0,1] op_sel_hi:[1,0,0]
	v_pk_mul_f32 v[58:59], v[50:51], v[76:77] op_sel_hi:[1,0]
	v_mov_b32_e32 v63, v57
	v_pk_fma_f32 v[64:65], v[50:51], v[68:69], v[58:59] op_sel:[0,0,1] op_sel_hi:[1,0,0] neg_lo:[0,0,1] neg_hi:[0,0,1]
	v_pk_fma_f32 v[50:51], v[50:51], v[68:69], v[58:59] op_sel:[0,0,1] op_sel_hi:[1,0,0]
	v_pk_mul_f32 v[58:59], v[52:53], v[74:75] op_sel_hi:[1,0]
	v_mov_b32_e32 v65, v51
	v_pk_fma_f32 v[68:69], v[52:53], v[66:67], v[58:59] op_sel:[0,0,1] op_sel_hi:[1,0,0] neg_lo:[0,0,1] neg_hi:[0,0,1]
	v_pk_fma_f32 v[52:53], v[52:53], v[66:67], v[58:59] op_sel:[0,0,1] op_sel_hi:[1,0,0]
	v_pk_mul_f32 v[56:57], v[172:173], v[62:63] op_sel_hi:[0,1]
	v_mov_b32_e32 v69, v53
	v_pk_mul_f32 v[52:53], v[172:173], v[64:65] op_sel_hi:[0,1]
	v_pk_mul_f32 v[54:55], v[172:173], v[60:61] op_sel_hi:[0,1]
	v_pk_mul_f32 v[58:59], v[172:173], v[68:69] op_sel_hi:[0,1]
	v_cvt_pk_bf16_f32 v50, v54, v55
	v_cvt_pk_bf16_f32 v51, v56, v57
	v_cvt_pk_bf16_f32 v52, v52, v53
	v_cvt_pk_bf16_f32 v53, v58, v59
	global_store_dwordx4 v[82:83], v[50:53], off offset:256 nt
	v_mov_b32_e32 v56, v143
	v_mov_b32_e32 v62, v145
	v_pk_mul_f32 v[52:53], v[46:47], v[138:139] op_sel_hi:[1,0]
	v_mad_i64_i32 v[50:51], s[12:13], v194, s44, v[204:205]
	v_pk_fma_f32 v[54:55], v[46:47], v[142:143], v[52:53] op_sel:[0,0,1] op_sel_hi:[1,0,0] neg_lo:[0,0,1] neg_hi:[0,0,1]
	v_pk_fma_f32 v[46:47], v[46:47], v[142:143], v[52:53] op_sel:[0,0,1] op_sel_hi:[1,0,0]
	v_lshl_add_u64 v[50:51], v[50:51], 0, v[206:207]
	v_mov_b32_e32 v46, v139
	v_pk_mul_f32 v[52:53], v[48:49], v[46:47] op_sel_hi:[1,0]
	v_mov_b32_e32 v55, v47
	v_pk_fma_f32 v[58:59], v[48:49], v[56:57], v[52:53] op_sel:[0,0,1] op_sel_hi:[1,0,0] neg_lo:[0,0,1] neg_hi:[0,0,1]
	v_pk_fma_f32 v[48:49], v[48:49], v[56:57], v[52:53] op_sel:[0,0,1] op_sel_hi:[1,0,0]
	v_pk_mul_f32 v[52:53], v[42:43], v[140:141] op_sel_hi:[1,0]
	v_mov_b32_e32 v48, v141
	v_pk_fma_f32 v[60:61], v[42:43], v[144:145], v[52:53] op_sel:[0,0,1] op_sel_hi:[1,0,0] neg_lo:[0,0,1] neg_hi:[0,0,1]
	v_pk_fma_f32 v[42:43], v[42:43], v[144:145], v[52:53] op_sel:[0,0,1] op_sel_hi:[1,0,0]
	v_pk_mul_f32 v[52:53], v[44:45], v[48:49] op_sel_hi:[1,0]
	v_mov_b32_e32 v59, v49
	v_pk_fma_f32 v[64:65], v[44:45], v[62:63], v[52:53] op_sel:[0,0,1] op_sel_hi:[1,0,0] neg_lo:[0,0,1] neg_hi:[0,0,1]
	v_pk_fma_f32 v[44:45], v[44:45], v[62:63], v[52:53] op_sel:[0,0,1] op_sel_hi:[1,0,0]
	v_mov_b32_e32 v61, v43
	v_pk_mul_f32 v[52:53], v[172:173], v[58:59] op_sel_hi:[0,1]
	v_pk_mul_f32 v[54:55], v[172:173], v[54:55] op_sel_hi:[0,1]
	v_mov_b32_e32 v65, v45
	v_pk_mul_f32 v[44:45], v[172:173], v[60:61] op_sel_hi:[0,1]
	v_cvt_pk_bf16_f32 v42, v54, v55
	v_cvt_pk_bf16_f32 v43, v52, v53
	v_pk_mul_f32 v[58:59], v[172:173], v[64:65] op_sel_hi:[0,1]
	v_cvt_pk_bf16_f32 v44, v44, v45
	v_cvt_pk_bf16_f32 v45, v58, v59
	global_store_dwordx4 v[50:51], v[42:45], off nt
	s_nop 1
	v_pk_mul_f32 v[42:43], v[38:39], v[138:139] op_sel_hi:[1,0]
	s_nop 0
	v_pk_fma_f32 v[44:45], v[38:39], v[142:143], v[42:43] op_sel:[0,0,1] op_sel_hi:[1,0,0] neg_lo:[0,0,1] neg_hi:[0,0,1]
	v_pk_fma_f32 v[38:39], v[38:39], v[142:143], v[42:43] op_sel:[0,0,1] op_sel_hi:[1,0,0]
	v_pk_mul_f32 v[42:43], v[40:41], v[46:47] op_sel_hi:[1,0]
	v_mov_b32_e32 v45, v39
	v_pk_fma_f32 v[46:47], v[40:41], v[56:57], v[42:43] op_sel:[0,0,1] op_sel_hi:[1,0,0] neg_lo:[0,0,1] neg_hi:[0,0,1]
	v_pk_fma_f32 v[40:41], v[40:41], v[56:57], v[42:43] op_sel:[0,0,1] op_sel_hi:[1,0,0]
	v_pk_mul_f32 v[42:43], v[34:35], v[140:141] op_sel_hi:[1,0]
	v_mov_b32_e32 v47, v41
	v_pk_fma_f32 v[52:53], v[34:35], v[144:145], v[42:43] op_sel:[0,0,1] op_sel_hi:[1,0,0] neg_lo:[0,0,1] neg_hi:[0,0,1]
	v_pk_fma_f32 v[34:35], v[34:35], v[144:145], v[42:43] op_sel:[0,0,1] op_sel_hi:[1,0,0]
	v_pk_mul_f32 v[42:43], v[36:37], v[48:49] op_sel_hi:[1,0]
	v_pk_mul_f32 v[40:41], v[172:173], v[46:47] op_sel_hi:[0,1]
	v_pk_fma_f32 v[48:49], v[36:37], v[62:63], v[42:43] op_sel:[0,0,1] op_sel_hi:[1,0,0] neg_lo:[0,0,1] neg_hi:[0,0,1]
	v_pk_fma_f32 v[36:37], v[36:37], v[62:63], v[42:43] op_sel:[0,0,1] op_sel_hi:[1,0,0]
	v_mov_b32_e32 v53, v35
	v_mov_b32_e32 v49, v37
	v_pk_mul_f32 v[42:43], v[172:173], v[48:49] op_sel_hi:[0,1]
	v_cndmask_b32_e64 v48, v138, v146, s[8:9]
	v_pk_mul_f32 v[38:39], v[172:173], v[44:45] op_sel_hi:[0,1]
	v_pk_mul_f32 v[36:37], v[172:173], v[52:53] op_sel_hi:[0,1]
	v_cvt_pk_bf16_f32 v34, v38, v39
	v_cvt_pk_bf16_f32 v35, v40, v41
	v_cndmask_b32_e64 v40, v142, v150, s[8:9]
	v_cndmask_b32_e64 v46, v139, v147, s[8:9]
	v_pk_mul_f32 v[52:53], v[30:31], v[48:49] op_sel_hi:[1,0]
	v_cvt_pk_bf16_f32 v36, v36, v37
	v_cndmask_b32_e64 v38, v143, v151, s[8:9]
	v_cndmask_b32_e64 v44, v140, v148, s[8:9]
	v_pk_fma_f32 v[54:55], v[30:31], v[40:41], v[52:53] op_sel:[0,0,1] op_sel_hi:[1,0,0] neg_lo:[0,0,1] neg_hi:[0,0,1]
	v_pk_fma_f32 v[30:31], v[30:31], v[40:41], v[52:53] op_sel:[0,0,1] op_sel_hi:[1,0,0]
	v_pk_mul_f32 v[52:53], v[32:33], v[46:47] op_sel_hi:[1,0]
; __device__ __forceinline__ unsigned cvt_pk_bf16(float lo, float hi) { unsigned r; asm volatile("v_cvt_pk_bf16_f32 %0, %1, %2" : "=v"(r) : "v"(lo), "v"(hi)); return r; }
;     __device__ __forceinline__ void operator()(const f32x4 (&acc)[2][2][4][2], const Unit& u, int wr, int wc, int fr, int fq) const {
;     ...
; #pragma unroll
;             for (int ai = 0; ai < 2; ++ai)
; #pragma unroll
;                 for (int m = 0; m < 4; ++m) {
;                     const int r = row0 + ai * HALF + m * 16;
;                     const f32x4 cs = colh ? csA[m] : csA[ai], sn = colh ? snA[m] : snA[ai];
;                     bf16_t* rowp = P + (size_t)r * ldp + col0;
; #pragma unroll
;                     for (int bj = 0; bj < 2; ++bj) {
;                         const f32x4 v0 = acc[ai][bj][m][0], v1 = acc[ai][bj][m][1]; f32x4 o0, o1;
;                         o0[0] = v0[0] * cs[0] - v0[1] * sn[0]; o0[1] = v0[0] * sn[0] + v0[1] * cs[0];
;                         o0[2] = v0[2] * cs[1] - v0[3] * sn[1]; o0[3] = v0[2] * sn[1] + v0[3] * cs[1];
;                         o1[0] = v1[0] * cs[2] - v1[1] * sn[2]; o1[1] = v1[0] * sn[2] + v1[1] * cs[2];
;                         o1[2] = v1[2] * cs[3] - v1[3] * sn[3]; o1[3] = v1[2] * sn[3] + v1[3] * cs[3];
;                         o0 = o0 * s; o1 = o1 * s;
;                         u32x4 w; w.x = cvt_pk_bf16(o0[0], o0[1]); w.y = cvt_pk_bf16(o0[2], o0[3]); w.z = cvt_pk_bf16(o1[0], o1[1]); w.w = cvt_pk_bf16(o1[2], o1[3]);
;                         *(u32x4*)(rowp + bj * HALF) = w; }
;                 }
	v_cvt_pk_bf16_f32 v37, v42, v43
	global_store_dwordx4 v[50:51], v[34:37], off offset:256 nt
	v_cndmask_b32_e64 v42, v141, v149, s[8:9]
	v_pk_fma_f32 v[56:57], v[32:33], v[38:39], v[52:53] op_sel:[0,0,1] op_sel_hi:[1,0,0] neg_lo:[0,0,1] neg_hi:[0,0,1]
	v_cndmask_b32_e64 v36, v144, v152, s[8:9]
	v_pk_fma_f32 v[32:33], v[32:33], v[38:39], v[52:53] op_sel:[0,0,1] op_sel_hi:[1,0,0]
	v_pk_mul_f32 v[52:53], v[26:27], v[44:45] op_sel_hi:[1,0]
	v_add_u32_e32 v35, 0xa0, v192
	v_cndmask_b32_e64 v34, v145, v153, s[8:9]
	v_pk_fma_f32 v[58:59], v[26:27], v[36:37], v[52:53] op_sel:[0,0,1] op_sel_hi:[1,0,0] neg_lo:[0,0,1] neg_hi:[0,0,1]
	v_pk_fma_f32 v[26:27], v[26:27], v[36:37], v[52:53] op_sel:[0,0,1] op_sel_hi:[1,0,0]
	v_pk_mul_f32 v[52:53], v[28:29], v[42:43] op_sel_hi:[1,0]
	v_mad_i64_i32 v[50:51], s[12:13], v35, s44, v[204:205]
	v_pk_fma_f32 v[60:61], v[28:29], v[34:35], v[52:53] op_sel:[0,0,1] op_sel_hi:[1,0,0] neg_lo:[0,0,1] neg_hi:[0,0,1]
	v_pk_fma_f32 v[28:29], v[28:29], v[34:35], v[52:53] op_sel:[0,0,1] op_sel_hi:[1,0,0]
	v_mov_b32_e32 v57, v33
	v_mov_b32_e32 v55, v31
	v_mov_b32_e32 v59, v27
	v_lshl_add_u64 v[50:51], v[50:51], 0, v[206:207]
	v_pk_mul_f32 v[32:33], v[172:173], v[56:57] op_sel_hi:[0,1]
	v_pk_mul_f32 v[30:31], v[172:173], v[54:55] op_sel_hi:[0,1]
	v_mov_b32_e32 v61, v29
	v_pk_mul_f32 v[28:29], v[172:173], v[58:59] op_sel_hi:[0,1]
	v_cvt_pk_bf16_f32 v26, v30, v31
	v_cvt_pk_bf16_f32 v27, v32, v33
	v_pk_mul_f32 v[52:53], v[172:173], v[60:61] op_sel_hi:[0,1]
	v_cvt_pk_bf16_f32 v28, v28, v29
	v_cvt_pk_bf16_f32 v29, v52, v53
	global_store_dwordx4 v[50:51], v[26:29], off nt
	s_nop 1
	v_pk_mul_f32 v[26:27], v[22:23], v[48:49] op_sel_hi:[1,0]
	s_nop 0
	v_pk_fma_f32 v[28:29], v[22:23], v[40:41], v[26:27] op_sel:[0,0,1] op_sel_hi:[1,0,0] neg_lo:[0,0,1] neg_hi:[0,0,1]
	v_pk_fma_f32 v[22:23], v[22:23], v[40:41], v[26:27] op_sel:[0,0,1] op_sel_hi:[1,0,0]
	v_pk_mul_f32 v[26:27], v[24:25], v[46:47] op_sel_hi:[1,0]
	v_mov_b32_e32 v29, v23
	v_pk_fma_f32 v[30:31], v[24:25], v[38:39], v[26:27] op_sel:[0,0,1] op_sel_hi:[1,0,0] neg_lo:[0,0,1] neg_hi:[0,0,1]
	v_pk_fma_f32 v[24:25], v[24:25], v[38:39], v[26:27] op_sel:[0,0,1] op_sel_hi:[1,0,0]
	v_pk_mul_f32 v[26:27], v[18:19], v[44:45] op_sel_hi:[1,0]
	v_mov_b32_e32 v31, v25
	v_pk_fma_f32 v[32:33], v[18:19], v[36:37], v[26:27] op_sel:[0,0,1] op_sel_hi:[1,0,0] neg_lo:[0,0,1] neg_hi:[0,0,1]
	v_pk_fma_f32 v[18:19], v[18:19], v[36:37], v[26:27] op_sel:[0,0,1] op_sel_hi:[1,0,0]
	v_pk_mul_f32 v[26:27], v[20:21], v[42:43] op_sel_hi:[1,0]
	v_mov_b32_e32 v33, v19
	v_pk_fma_f32 v[36:37], v[20:21], v[34:35], v[26:27] op_sel:[0,0,1] op_sel_hi:[1,0,0] neg_lo:[0,0,1] neg_hi:[0,0,1]
	v_pk_fma_f32 v[20:21], v[20:21], v[34:35], v[26:27] op_sel:[0,0,1] op_sel_hi:[1,0,0]
	v_pk_mul_f32 v[24:25], v[172:173], v[30:31] op_sel_hi:[0,1]
	v_mov_b32_e32 v37, v21
	v_pk_mul_f32 v[20:21], v[172:173], v[32:33] op_sel_hi:[0,1]
	v_cndmask_b32_e64 v32, v138, v130, s[8:9]
	v_pk_mul_f32 v[22:23], v[172:173], v[28:29] op_sel_hi:[0,1]
	v_pk_mul_f32 v[26:27], v[172:173], v[36:37] op_sel_hi:[0,1]
	v_cvt_pk_bf16_f32 v18, v22, v23
	v_cvt_pk_bf16_f32 v19, v24, v25
	v_cndmask_b32_e64 v24, v142, v134, s[8:9]
	v_cndmask_b32_e64 v30, v139, v131, s[8:9]
	v_pk_mul_f32 v[36:37], v[14:15], v[32:33] op_sel_hi:[1,0]
	v_cvt_pk_bf16_f32 v20, v20, v21
	v_cndmask_b32_e64 v22, v143, v135, s[8:9]
	v_cndmask_b32_e64 v28, v140, v132, s[8:9]
	v_pk_fma_f32 v[38:39], v[14:15], v[24:25], v[36:37] op_sel:[0,0,1] op_sel_hi:[1,0,0] neg_lo:[0,0,1] neg_hi:[0,0,1]
	v_pk_fma_f32 v[14:15], v[14:15], v[24:25], v[36:37] op_sel:[0,0,1] op_sel_hi:[1,0,0]
	v_pk_mul_f32 v[36:37], v[16:17], v[30:31] op_sel_hi:[1,0]
	v_cvt_pk_bf16_f32 v21, v26, v27
	global_store_dwordx4 v[50:51], v[18:21], off offset:256 nt
	v_cndmask_b32_e64 v26, v141, v133, s[8:9]
	v_pk_fma_f32 v[40:41], v[16:17], v[22:23], v[36:37] op_sel:[0,0,1] op_sel_hi:[1,0,0] neg_lo:[0,0,1] neg_hi:[0,0,1]
	v_cndmask_b32_e64 v20, v144, v136, s[8:9]
	v_pk_fma_f32 v[16:17], v[16:17], v[22:23], v[36:37] op_sel:[0,0,1] op_sel_hi:[1,0,0]
	v_pk_mul_f32 v[36:37], v[10:11], v[28:29] op_sel_hi:[1,0]
	v_add_u32_e32 v19, 0xb0, v192
	v_cndmask_b32_e64 v18, v145, v137, s[8:9]
	v_pk_fma_f32 v[42:43], v[10:11], v[20:21], v[36:37] op_sel:[0,0,1] op_sel_hi:[1,0,0] neg_lo:[0,0,1] neg_hi:[0,0,1]
	v_pk_fma_f32 v[10:11], v[10:11], v[20:21], v[36:37] op_sel:[0,0,1] op_sel_hi:[1,0,0]
	v_pk_mul_f32 v[36:37], v[12:13], v[26:27] op_sel_hi:[1,0]
	v_mad_i64_i32 v[34:35], s[12:13], v19, s44, v[204:205]
	v_pk_fma_f32 v[44:45], v[12:13], v[18:19], v[36:37] op_sel:[0,0,1] op_sel_hi:[1,0,0] neg_lo:[0,0,1] neg_hi:[0,0,1]
	v_pk_fma_f32 v[12:13], v[12:13], v[18:19], v[36:37] op_sel:[0,0,1] op_sel_hi:[1,0,0]
	v_mov_b32_e32 v41, v17
	v_mov_b32_e32 v39, v15
	v_mov_b32_e32 v43, v11
	v_lshl_add_u64 v[34:35], v[34:35], 0, v[206:207]
	v_pk_mul_f32 v[16:17], v[172:173], v[40:41] op_sel_hi:[0,1]
	v_pk_mul_f32 v[14:15], v[172:173], v[38:39] op_sel_hi:[0,1]
	v_mov_b32_e32 v45, v13
	v_pk_mul_f32 v[12:13], v[172:173], v[42:43] op_sel_hi:[0,1]
	v_cvt_pk_bf16_f32 v10, v14, v15
	v_cvt_pk_bf16_f32 v11, v16, v17
	v_pk_mul_f32 v[36:37], v[172:173], v[44:45] op_sel_hi:[0,1]
	v_cvt_pk_bf16_f32 v12, v12, v13
	v_cvt_pk_bf16_f32 v13, v36, v37
	global_store_dwordx4 v[34:35], v[10:13], off nt
	s_nop 1
	v_pk_mul_f32 v[10:11], v[6:7], v[32:33] op_sel_hi:[1,0]
	s_nop 0
	v_pk_fma_f32 v[12:13], v[6:7], v[24:25], v[10:11] op_sel:[0,0,1] op_sel_hi:[1,0,0] neg_lo:[0,0,1] neg_hi:[0,0,1]
	v_pk_fma_f32 v[6:7], v[6:7], v[24:25], v[10:11] op_sel:[0,0,1] op_sel_hi:[1,0,0]
	v_pk_mul_f32 v[10:11], v[8:9], v[30:31] op_sel_hi:[1,0]
	v_mov_b32_e32 v13, v7
	v_pk_fma_f32 v[14:15], v[8:9], v[22:23], v[10:11] op_sel:[0,0,1] op_sel_hi:[1,0,0] neg_lo:[0,0,1] neg_hi:[0,0,1]
	v_pk_fma_f32 v[8:9], v[8:9], v[22:23], v[10:11] op_sel:[0,0,1] op_sel_hi:[1,0,0]
	v_pk_mul_f32 v[10:11], v[2:3], v[28:29] op_sel_hi:[1,0]
	v_mov_b32_e32 v15, v9
	v_pk_fma_f32 v[16:17], v[2:3], v[20:21], v[10:11] op_sel:[0,0,1] op_sel_hi:[1,0,0] neg_lo:[0,0,1] neg_hi:[0,0,1]
	v_pk_fma_f32 v[2:3], v[2:3], v[20:21], v[10:11] op_sel:[0,0,1] op_sel_hi:[1,0,0]
	v_pk_mul_f32 v[10:11], v[4:5], v[26:27] op_sel_hi:[1,0]
	v_mov_b32_e32 v17, v3
	v_pk_fma_f32 v[20:21], v[4:5], v[18:19], v[10:11] op_sel:[0,0,1] op_sel_hi:[1,0,0] neg_lo:[0,0,1] neg_hi:[0,0,1]
	v_pk_fma_f32 v[4:5], v[4:5], v[18:19], v[10:11] op_sel:[0,0,1] op_sel_hi:[1,0,0]
	v_pk_mul_f32 v[8:9], v[172:173], v[14:15] op_sel_hi:[0,1]
	v_mov_b32_e32 v21, v5
	v_pk_mul_f32 v[4:5], v[172:173], v[16:17] op_sel_hi:[0,1]
	v_pk_mul_f32 v[6:7], v[172:173], v[12:13] op_sel_hi:[0,1]
	v_pk_mul_f32 v[10:11], v[172:173], v[20:21] op_sel_hi:[0,1]
	v_cvt_pk_bf16_f32 v2, v6, v7
	v_cvt_pk_bf16_f32 v3, v8, v9
	v_cvt_pk_bf16_f32 v4, v4, v5
	v_cvt_pk_bf16_f32 v5, v10, v11
	global_store_dwordx4 v[34:35], v[2:5], off offset:256 nt
	s_andn2_b64 vcc, exec, s[10:11]
	s_mov_b64 s[10:11], -1
	s_cbranch_vccnz .LBB0_251
